# stack1 + SGPR-base form for all four GEMM epilogue stores (5 source dwords per store instead of 6)
# baseline (speedup 1.0000x reference)
; __device__ __forceinline__ unsigned cvt_pk_bf16(float lo, float hi) { unsigned r; asm volatile("v_cvt_pk_bf16_f32 %0, %1, %2" : "=v"(r) : "v"(lo), "v"(hi)); return r; }
;     __device__ __forceinline__ void operator()(const f32x4 (&acc)[2][2][4][2], const Unit& u, int wr, int wc, int fr, int fq, const float (&rsv)[8]) const {
;         const int row0 = u.pm * BM + wr * 64 + fr, col0 = u.pn * BM + wc * 32 + 8 * fq;
;         const bool isq = (u.pn < 2) || (u.pn == 6) || (u.pn == 7);
;         const float sc = isq ? QSCALE : 1.f;
;         const bool rotw = (u.pn < 4) && ((wc & 1) == 0);
;         const float sgn = (fq == 0) ? -1.f : 1.f; const bool rotl = fq < 2; const int pidx = (((fq ^ 1) << 4) | fr) << 2;
; #pragma unroll
;         for (int ai = 0; ai < 2; ++ai)
; #pragma unroll
;             for (int m = 0; m < 4; ++m) { const int row = row0 + ai * HALF + m * 16; bf16_t* rowp = O + (size_t)row * 3072 + col0; const float scr_ = sc * rsv[ai * 4 + m];
;                 f32x4 c0 = {1.f, 1.f, 1.f, 1.f}, c1 = c0, s0 = {0.f, 0.f, 0.f, 0.f}, s1 = s0;
;                 if (rotw) { const f32x4* rp = (const f32x4*)(rot + (size_t)row * 16); c0 = rp[0]; c1 = rp[1]; s0 = rp[2]; s1 = rp[3]; }
; #pragma unroll
;                 for (int bj = 0; bj < 2; ++bj) { f32x4 v0 = acc[ai][bj][m][0], v1 = acc[ai][bj][m][1];
;                     if (rotw) { f32x4 p0, p1;
; #pragma unroll
;                         for (int j = 0; j < 4; ++j) { const float a0 = v0[j], a1 = v1[j]; p0[j] = __int_as_float(__builtin_amdgcn_ds_bpermute(pidx, __float_as_int(a0))); p1[j] = __int_as_float(__builtin_amdgcn_ds_bpermute(pidx, __float_as_int(a1))); }
;                         if (rotl) { v0 = v0 * c0 + (p0 * s0) * sgn; v1 = v1 * c1 + (p1 * s1) * sgn; } }
;                     v0 = v0 * scr_; v1 = v1 * scr_; u32x4 w; w.x = cvt_pk_bf16(v0[0], v0[1]); w.y = cvt_pk_bf16(v0[2], v0[3]); w.z = cvt_pk_bf16(v1[0], v1[1]); w.w = cvt_pk_bf16(v1[2], v1[3]);
;                     *(u32x4*)(rowp + bj * HALF) = w; } }
.LBB0_101:
	s_cmp_lt_i32 s76, 2
	s_cselect_b64 s[42:43], -1, 0
	s_and_b32 s11, s76, -2
	s_cmp_eq_u32 s11, 6
	s_cselect_b64 s[58:59], -1, 0
	s_or_b64 vcc, s[42:43], s[58:59]
	v_cndmask_b32_e32 v161, 1.0, v238, vcc
	s_waitcnt lgkmcnt(0)
	v_lshl_or_b32 v162, s76, 8, v172
	v_mov_b64_e32 v[164:165], s[14:15]
	s_waitcnt vmcnt(8)
	v_mul_f32_e32 v166, v161, v182
	v_ashrrev_i32_e32 v163, 31, v162
	v_mad_i64_i32 v[164:165], s[42:43], v160, s97, v[164:165]
	v_lshl_add_u64 v[164:165], v[162:163], 1, v[164:165]
	v_pk_mul_f32 v[168:169], v[166:167], v[124:125] op_sel_hi:[0,1]
	v_pk_mul_f32 v[124:125], v[166:167], v[122:123] op_sel_hi:[0,1]
	s_and_b64 vcc, exec, s[6:7]
	v_pk_mul_f32 v[128:129], v[166:167], v[128:129] op_sel_hi:[0,1]
	v_pk_mul_f32 v[126:127], v[166:167], v[126:127] op_sel_hi:[0,1]
	v_cvt_pk_bf16_f32 v122, v126, v127
	v_cvt_pk_bf16_f32 v123, v128, v129
	v_cvt_pk_bf16_f32 v124, v124, v125
	v_cvt_pk_bf16_f32 v125, v168, v169
	v_subrev_u32_e32 v239, s14, v164
	global_store_dwordx4 v239, v[122:125], s[14:15]
	s_cbranch_vccnz .LBB0_105
	ds_bpermute_b32 v126, v173, v118
	ds_bpermute_b32 v122, v173, v114
	ds_bpermute_b32 v127, v173, v119
	ds_bpermute_b32 v123, v173, v115
	ds_bpermute_b32 v128, v173, v120
	ds_bpermute_b32 v124, v173, v116
	ds_bpermute_b32 v129, v173, v121
	ds_bpermute_b32 v125, v173, v117
	s_and_saveexec_b64 s[76:77], s[8:9]
	s_cbranch_execz .LBB0_104
	s_waitcnt lgkmcnt(1)
	v_pk_mul_f32 v[128:129], v[144:145], v[128:129]
	v_pk_mul_f32 v[126:127], v[142:143], v[126:127]
	s_waitcnt lgkmcnt(0)
	v_pk_mul_f32 v[124:125], v[140:141], v[124:125]
	v_pk_mul_f32 v[122:123], v[138:139], v[122:123]
	v_pk_mul_f32 v[128:129], v[154:155], v[128:129]
	v_pk_mul_f32 v[126:127], v[152:153], v[126:127]
	v_pk_mul_f32 v[124:125], v[154:155], v[124:125]
	v_pk_mul_f32 v[122:123], v[152:153], v[122:123]
	v_pk_fma_f32 v[120:121], v[120:121], v[136:137], v[128:129]
	v_pk_fma_f32 v[118:119], v[118:119], v[134:135], v[126:127]
	v_pk_fma_f32 v[116:117], v[116:117], v[132:133], v[124:125]
	v_pk_fma_f32 v[114:115], v[114:115], v[130:131], v[122:123]

; __device__ __forceinline__ unsigned cvt_pk_bf16(float lo, float hi) { unsigned r; asm volatile("v_cvt_pk_bf16_f32 %0, %1, %2" : "=v"(r) : "v"(lo), "v"(hi)); return r; }
;     __device__ __forceinline__ void operator()(const f32x4 (&acc)[2][2][4][2], const Unit& u, int wr, int wc, int fr, int fq, const float (&rsv)[8]) const {
;     ...
;             for (int m = 0; m < 4; ++m) { const int row = row0 + ai * HALF + m * 16; bf16_t* rowp = O + (size_t)row * 3072 + col0; const float scr_ = sc * rsv[ai * 4 + m];
;                 f32x4 c0 = {1.f, 1.f, 1.f, 1.f}, c1 = c0, s0 = {0.f, 0.f, 0.f, 0.f}, s1 = s0;
;                 if (rotw) { const f32x4* rp = (const f32x4*)(rot + (size_t)row * 16); c0 = rp[0]; c1 = rp[1]; s0 = rp[2]; s1 = rp[3]; }
; #pragma unroll
;                 for (int bj = 0; bj < 2; ++bj) { f32x4 v0 = acc[ai][bj][m][0], v1 = acc[ai][bj][m][1];
;                     if (rotw) { f32x4 p0, p1;
; #pragma unroll
;                         for (int j = 0; j < 4; ++j) { const float a0 = v0[j], a1 = v1[j]; p0[j] = __int_as_float(__builtin_amdgcn_ds_bpermute(pidx, __float_as_int(a0))); p1[j] = __int_as_float(__builtin_amdgcn_ds_bpermute(pidx, __float_as_int(a1))); }
;                         if (rotl) { v0 = v0 * c0 + (p0 * s0) * sgn; v1 = v1 * c1 + (p1 * s1) * sgn; } }
;                     v0 = v0 * scr_; v1 = v1 * scr_; u32x4 w; w.x = cvt_pk_bf16(v0[0], v0[1]); w.y = cvt_pk_bf16(v0[2], v0[3]); w.z = cvt_pk_bf16(v1[0], v1[1]); w.w = cvt_pk_bf16(v1[2], v1[3]);
;                     *(u32x4*)(rowp + bj * HALF) = w; } }
.LBB0_105:
	v_mov_b32_e32 v167, v166
	s_waitcnt lgkmcnt(6)
	v_mov_b32_e32 v122, v166
	s_waitcnt lgkmcnt(4)
	v_mov_b32_e32 v123, v166
	v_or_b32_e32 v130, 16, v160
	v_pk_mul_f32 v[120:121], v[122:123], v[120:121]
	v_pk_mul_f32 v[122:123], v[122:123], v[116:117]
	v_pk_mul_f32 v[116:117], v[166:167], v[114:115]
	s_and_b64 vcc, exec, s[6:7]
	v_ashrrev_i32_e32 v131, 31, v130
	v_pk_mul_f32 v[118:119], v[166:167], v[118:119]
	s_nop 0
	v_cvt_pk_bf16_f32 v114, v118, v119
	v_cvt_pk_bf16_f32 v115, v120, v121
	v_cvt_pk_bf16_f32 v116, v116, v117
	v_cvt_pk_bf16_f32 v117, v122, v123
	v_subrev_u32_e32 v239, s14, v164
	global_store_dwordx4 v239, v[114:117], s[14:15] offset:256
	s_cbranch_vccnz .LBB0_107
	s_nop 0
	v_lshlrev_b64 v[114:115], 6, v[130:131]
	v_lshl_add_u64 v[122:123], s[16:17], 0, v[114:115]
	global_load_dwordx4 v[118:121], v[122:123], off
	global_load_dwordx4 v[114:117], v[122:123], off offset:16
	s_waitcnt lgkmcnt(1)
	global_load_dwordx4 v[126:129], v[122:123], off offset:32
	s_waitcnt lgkmcnt(0)
	global_load_dwordx4 v[122:125], v[122:123], off offset:48
	s_and_b64 vcc, exec, s[6:7]
	s_cbranch_vccz .LBB0_108
	s_branch .LBB0_111

; __device__ __forceinline__ unsigned cvt_pk_bf16(float lo, float hi) { unsigned r; asm volatile("v_cvt_pk_bf16_f32 %0, %1, %2" : "=v"(r) : "v"(lo), "v"(hi)); return r; }
;     __device__ __forceinline__ void operator()(const f32x4 (&acc)[2][2][4][2], const Unit& u, int wr, int wc, int fr, int fq, const float (&rsv)[8]) const {
;         const int row0 = u.pm * BM + wr * 64 + fr, col0 = u.pn * BM + wc * 32 + 8 * fq;
;         const bool isq = (u.pn < 2) || (u.pn == 6) || (u.pn == 7);
;         const float sc = isq ? QSCALE : 1.f;
;         const bool rotw = (u.pn < 4) && ((wc & 1) == 0);
;         const float sgn = (fq == 0) ? -1.f : 1.f; const bool rotl = fq < 2; const int pidx = (((fq ^ 1) << 4) | fr) << 2;
; #pragma unroll
;         for (int ai = 0; ai < 2; ++ai)
; #pragma unroll
;             for (int m = 0; m < 4; ++m) { const int row = row0 + ai * HALF + m * 16; bf16_t* rowp = O + (size_t)row * 3072 + col0; const float scr_ = sc * rsv[ai * 4 + m];
;                 f32x4 c0 = {1.f, 1.f, 1.f, 1.f}, c1 = c0, s0 = {0.f, 0.f, 0.f, 0.f}, s1 = s0;
;                 if (rotw) { const f32x4* rp = (const f32x4*)(rot + (size_t)row * 16); c0 = rp[0]; c1 = rp[1]; s0 = rp[2]; s1 = rp[3]; }
; #pragma unroll
;                 for (int bj = 0; bj < 2; ++bj) { f32x4 v0 = acc[ai][bj][m][0], v1 = acc[ai][bj][m][1];
;                     if (rotw) { f32x4 p0, p1;
; #pragma unroll
;                         for (int j = 0; j < 4; ++j) { const float a0 = v0[j], a1 = v1[j]; p0[j] = __int_as_float(__builtin_amdgcn_ds_bpermute(pidx, __float_as_int(a0))); p1[j] = __int_as_float(__builtin_amdgcn_ds_bpermute(pidx, __float_as_int(a1))); }
;                         if (rotl) { v0 = v0 * c0 + (p0 * s0) * sgn; v1 = v1 * c1 + (p1 * s1) * sgn; } }
;                     v0 = v0 * scr_; v1 = v1 * scr_; u32x4 w; w.x = cvt_pk_bf16(v0[0], v0[1]); w.y = cvt_pk_bf16(v0[2], v0[3]); w.z = cvt_pk_bf16(v1[0], v1[1]); w.w = cvt_pk_bf16(v1[2], v1[3]);
;                     *(u32x4*)(rowp + bj * HALF) = w; } }
.LBB0_111:
	s_waitcnt lgkmcnt(0)
	v_mov_b64_e32 v[134:135], s[14:15]
	v_mul_f32_e32 v132, v161, v181
	v_mad_i64_i32 v[130:131], s[42:43], v130, s97, v[134:135]
	v_lshl_add_u64 v[130:131], v[162:163], 1, v[130:131]
	v_pk_mul_f32 v[134:135], v[132:133], v[108:109] op_sel_hi:[0,1]
	v_pk_mul_f32 v[108:109], v[132:133], v[106:107] op_sel_hi:[0,1]
	s_and_b64 vcc, exec, s[6:7]
	v_pk_mul_f32 v[112:113], v[132:133], v[112:113] op_sel_hi:[0,1]
	v_pk_mul_f32 v[110:111], v[132:133], v[110:111] op_sel_hi:[0,1]
	v_cvt_pk_bf16_f32 v106, v110, v111
	v_cvt_pk_bf16_f32 v107, v112, v113
	v_cvt_pk_bf16_f32 v108, v108, v109
	v_cvt_pk_bf16_f32 v109, v134, v135
	v_subrev_u32_e32 v239, s14, v130
	global_store_dwordx4 v239, v[106:109], s[14:15]
	s_cbranch_vccnz .LBB0_115
	ds_bpermute_b32 v110, v173, v102
	ds_bpermute_b32 v106, v173, v98
	ds_bpermute_b32 v111, v173, v103
	ds_bpermute_b32 v107, v173, v99
	ds_bpermute_b32 v112, v173, v104
	ds_bpermute_b32 v108, v173, v100
	ds_bpermute_b32 v113, v173, v105
	ds_bpermute_b32 v109, v173, v101
	s_and_saveexec_b64 s[76:77], s[8:9]
	s_cbranch_execz .LBB0_114
	s_waitcnt vmcnt(2) lgkmcnt(1)
	v_pk_mul_f32 v[112:113], v[128:129], v[112:113]
	v_pk_mul_f32 v[110:111], v[126:127], v[110:111]
	s_waitcnt vmcnt(1) lgkmcnt(0)
	v_pk_mul_f32 v[108:109], v[124:125], v[108:109]
	v_pk_mul_f32 v[106:107], v[122:123], v[106:107]
	v_pk_mul_f32 v[112:113], v[154:155], v[112:113]
	v_pk_mul_f32 v[110:111], v[152:153], v[110:111]
	v_pk_mul_f32 v[108:109], v[154:155], v[108:109]
	v_pk_mul_f32 v[106:107], v[152:153], v[106:107]
	v_pk_fma_f32 v[104:105], v[104:105], v[120:121], v[112:113]
	v_pk_fma_f32 v[102:103], v[102:103], v[118:119], v[110:111]
	v_pk_fma_f32 v[100:101], v[100:101], v[116:117], v[108:109]
	v_pk_fma_f32 v[98:99], v[98:99], v[114:115], v[106:107]

; __device__ __forceinline__ unsigned cvt_pk_bf16(float lo, float hi) { unsigned r; asm volatile("v_cvt_pk_bf16_f32 %0, %1, %2" : "=v"(r) : "v"(lo), "v"(hi)); return r; }
;     __device__ __forceinline__ void operator()(const f32x4 (&acc)[2][2][4][2], const Unit& u, int wr, int wc, int fr, int fq, const float (&rsv)[8]) const {
;     ...
;             for (int m = 0; m < 4; ++m) { const int row = row0 + ai * HALF + m * 16; bf16_t* rowp = O + (size_t)row * 3072 + col0; const float scr_ = sc * rsv[ai * 4 + m];
;                 f32x4 c0 = {1.f, 1.f, 1.f, 1.f}, c1 = c0, s0 = {0.f, 0.f, 0.f, 0.f}, s1 = s0;
;                 if (rotw) { const f32x4* rp = (const f32x4*)(rot + (size_t)row * 16); c0 = rp[0]; c1 = rp[1]; s0 = rp[2]; s1 = rp[3]; }
; #pragma unroll
;                 for (int bj = 0; bj < 2; ++bj) { f32x4 v0 = acc[ai][bj][m][0], v1 = acc[ai][bj][m][1];
;                     if (rotw) { f32x4 p0, p1;
; #pragma unroll
;                         for (int j = 0; j < 4; ++j) { const float a0 = v0[j], a1 = v1[j]; p0[j] = __int_as_float(__builtin_amdgcn_ds_bpermute(pidx, __float_as_int(a0))); p1[j] = __int_as_float(__builtin_amdgcn_ds_bpermute(pidx, __float_as_int(a1))); }
;                         if (rotl) { v0 = v0 * c0 + (p0 * s0) * sgn; v1 = v1 * c1 + (p1 * s1) * sgn; } }
;                     v0 = v0 * scr_; v1 = v1 * scr_; u32x4 w; w.x = cvt_pk_bf16(v0[0], v0[1]); w.y = cvt_pk_bf16(v0[2], v0[3]); w.z = cvt_pk_bf16(v1[0], v1[1]); w.w = cvt_pk_bf16(v1[2], v1[3]);
;                     *(u32x4*)(rowp + bj * HALF) = w; } }
.LBB0_115:
	v_mov_b32_e32 v133, v132
	s_waitcnt lgkmcnt(6)
	v_mov_b32_e32 v106, v132
	s_waitcnt lgkmcnt(4)
	v_mov_b32_e32 v107, v132
	s_waitcnt vmcnt(3)
	v_or_b32_e32 v114, 32, v160
	v_pk_mul_f32 v[104:105], v[106:107], v[104:105]
	v_pk_mul_f32 v[106:107], v[106:107], v[100:101]
	v_pk_mul_f32 v[100:101], v[132:133], v[98:99]
	s_and_b64 vcc, exec, s[6:7]
	v_ashrrev_i32_e32 v115, 31, v114
	v_pk_mul_f32 v[102:103], v[132:133], v[102:103]
	s_nop 0
	v_cvt_pk_bf16_f32 v98, v102, v103
	v_cvt_pk_bf16_f32 v99, v104, v105
	v_cvt_pk_bf16_f32 v100, v100, v101
	v_cvt_pk_bf16_f32 v101, v106, v107
	v_subrev_u32_e32 v239, s14, v130
	global_store_dwordx4 v239, v[98:101], s[14:15] offset:256
	s_cbranch_vccnz .LBB0_117
	s_nop 0
	v_lshlrev_b64 v[98:99], 6, v[114:115]
	v_lshl_add_u64 v[106:107], s[16:17], 0, v[98:99]
	global_load_dwordx4 v[102:105], v[106:107], off
	global_load_dwordx4 v[98:101], v[106:107], off offset:16
	s_waitcnt lgkmcnt(1)
	global_load_dwordx4 v[110:113], v[106:107], off offset:32
	s_waitcnt lgkmcnt(0)
	global_load_dwordx4 v[106:109], v[106:107], off offset:48
	s_and_b64 vcc, exec, s[6:7]
	s_cbranch_vccz .LBB0_118
	s_branch .LBB0_121

; __device__ __forceinline__ unsigned cvt_pk_bf16(float lo, float hi) { unsigned r; asm volatile("v_cvt_pk_bf16_f32 %0, %1, %2" : "=v"(r) : "v"(lo), "v"(hi)); return r; }
;     __device__ __forceinline__ void operator()(const f32x4 (&acc)[2][2][4][2], const Unit& u, int wr, int wc, int fr, int fq, const float (&rsv)[8]) const {
;         const int row0 = u.pm * BM + wr * 64 + fr, col0 = u.pn * BM + wc * 32 + 8 * fq;
;         const bool isq = (u.pn < 2) || (u.pn == 6) || (u.pn == 7);
;         const float sc = isq ? QSCALE : 1.f;
;         const bool rotw = (u.pn < 4) && ((wc & 1) == 0);
;         const float sgn = (fq == 0) ? -1.f : 1.f; const bool rotl = fq < 2; const int pidx = (((fq ^ 1) << 4) | fr) << 2;
; #pragma unroll
;         for (int ai = 0; ai < 2; ++ai)
; #pragma unroll
;             for (int m = 0; m < 4; ++m) { const int row = row0 + ai * HALF + m * 16; bf16_t* rowp = O + (size_t)row * 3072 + col0; const float scr_ = sc * rsv[ai * 4 + m];
;                 f32x4 c0 = {1.f, 1.f, 1.f, 1.f}, c1 = c0, s0 = {0.f, 0.f, 0.f, 0.f}, s1 = s0;
;                 if (rotw) { const f32x4* rp = (const f32x4*)(rot + (size_t)row * 16); c0 = rp[0]; c1 = rp[1]; s0 = rp[2]; s1 = rp[3]; }
; #pragma unroll
;                 for (int bj = 0; bj < 2; ++bj) { f32x4 v0 = acc[ai][bj][m][0], v1 = acc[ai][bj][m][1];
;                     if (rotw) { f32x4 p0, p1;
; #pragma unroll
;                         for (int j = 0; j < 4; ++j) { const float a0 = v0[j], a1 = v1[j]; p0[j] = __int_as_float(__builtin_amdgcn_ds_bpermute(pidx, __float_as_int(a0))); p1[j] = __int_as_float(__builtin_amdgcn_ds_bpermute(pidx, __float_as_int(a1))); }
;                         if (rotl) { v0 = v0 * c0 + (p0 * s0) * sgn; v1 = v1 * c1 + (p1 * s1) * sgn; } }
;                     v0 = v0 * scr_; v1 = v1 * scr_; u32x4 w; w.x = cvt_pk_bf16(v0[0], v0[1]); w.y = cvt_pk_bf16(v0[2], v0[3]); w.z = cvt_pk_bf16(v1[0], v1[1]); w.w = cvt_pk_bf16(v1[2], v1[3]);
;                     *(u32x4*)(rowp + bj * HALF) = w; } }
.LBB0_121:
	s_waitcnt lgkmcnt(0)
	v_mov_b64_e32 v[118:119], s[14:15]
	v_mul_f32_e32 v116, v161, v180
	v_mad_i64_i32 v[114:115], s[42:43], v114, s97, v[118:119]
	v_lshl_add_u64 v[114:115], v[162:163], 1, v[114:115]
	v_pk_mul_f32 v[118:119], v[116:117], v[92:93] op_sel_hi:[0,1]
	v_pk_mul_f32 v[92:93], v[116:117], v[90:91] op_sel_hi:[0,1]
	s_and_b64 vcc, exec, s[6:7]
	v_pk_mul_f32 v[96:97], v[116:117], v[96:97] op_sel_hi:[0,1]
	v_pk_mul_f32 v[94:95], v[116:117], v[94:95] op_sel_hi:[0,1]
	v_cvt_pk_bf16_f32 v90, v94, v95
	v_cvt_pk_bf16_f32 v91, v96, v97
	v_cvt_pk_bf16_f32 v92, v92, v93
	v_cvt_pk_bf16_f32 v93, v118, v119
	v_subrev_u32_e32 v239, s14, v114
	global_store_dwordx4 v239, v[90:93], s[14:15]
	s_cbranch_vccnz .LBB0_125
	ds_bpermute_b32 v94, v173, v86
	ds_bpermute_b32 v90, v173, v82
	ds_bpermute_b32 v95, v173, v87
	ds_bpermute_b32 v91, v173, v83
	ds_bpermute_b32 v96, v173, v88
	ds_bpermute_b32 v92, v173, v84
	ds_bpermute_b32 v97, v173, v89
	ds_bpermute_b32 v93, v173, v85
	s_and_saveexec_b64 s[76:77], s[8:9]
	s_cbranch_execz .LBB0_124
	s_waitcnt vmcnt(2) lgkmcnt(1)
	v_pk_mul_f32 v[96:97], v[112:113], v[96:97]
	v_pk_mul_f32 v[94:95], v[110:111], v[94:95]
	s_waitcnt vmcnt(1) lgkmcnt(0)
	v_pk_mul_f32 v[92:93], v[108:109], v[92:93]
	v_pk_mul_f32 v[90:91], v[106:107], v[90:91]
	v_pk_mul_f32 v[96:97], v[154:155], v[96:97]
	v_pk_mul_f32 v[94:95], v[152:153], v[94:95]
	v_pk_mul_f32 v[92:93], v[154:155], v[92:93]
	v_pk_mul_f32 v[90:91], v[152:153], v[90:91]
	v_pk_fma_f32 v[88:89], v[88:89], v[104:105], v[96:97]
	v_pk_fma_f32 v[86:87], v[86:87], v[102:103], v[94:95]
	v_pk_fma_f32 v[84:85], v[84:85], v[100:101], v[92:93]
	v_pk_fma_f32 v[82:83], v[82:83], v[98:99], v[90:91]

; __device__ __forceinline__ unsigned cvt_pk_bf16(float lo, float hi) { unsigned r; asm volatile("v_cvt_pk_bf16_f32 %0, %1, %2" : "=v"(r) : "v"(lo), "v"(hi)); return r; }
;     __device__ __forceinline__ void operator()(const f32x4 (&acc)[2][2][4][2], const Unit& u, int wr, int wc, int fr, int fq, const float (&rsv)[8]) const {
;     ...
;             for (int m = 0; m < 4; ++m) { const int row = row0 + ai * HALF + m * 16; bf16_t* rowp = O + (size_t)row * 3072 + col0; const float scr_ = sc * rsv[ai * 4 + m];
;                 f32x4 c0 = {1.f, 1.f, 1.f, 1.f}, c1 = c0, s0 = {0.f, 0.f, 0.f, 0.f}, s1 = s0;
;                 if (rotw) { const f32x4* rp = (const f32x4*)(rot + (size_t)row * 16); c0 = rp[0]; c1 = rp[1]; s0 = rp[2]; s1 = rp[3]; }
; #pragma unroll
;                 for (int bj = 0; bj < 2; ++bj) { f32x4 v0 = acc[ai][bj][m][0], v1 = acc[ai][bj][m][1];
;                     if (rotw) { f32x4 p0, p1;
; #pragma unroll
;                         for (int j = 0; j < 4; ++j) { const float a0 = v0[j], a1 = v1[j]; p0[j] = __int_as_float(__builtin_amdgcn_ds_bpermute(pidx, __float_as_int(a0))); p1[j] = __int_as_float(__builtin_amdgcn_ds_bpermute(pidx, __float_as_int(a1))); }
;                         if (rotl) { v0 = v0 * c0 + (p0 * s0) * sgn; v1 = v1 * c1 + (p1 * s1) * sgn; } }
;                     v0 = v0 * scr_; v1 = v1 * scr_; u32x4 w; w.x = cvt_pk_bf16(v0[0], v0[1]); w.y = cvt_pk_bf16(v0[2], v0[3]); w.z = cvt_pk_bf16(v1[0], v1[1]); w.w = cvt_pk_bf16(v1[2], v1[3]);
;                     *(u32x4*)(rowp + bj * HALF) = w; } }
.LBB0_125:
	v_mov_b32_e32 v117, v116
	s_waitcnt lgkmcnt(6)
	v_mov_b32_e32 v90, v116
	s_waitcnt lgkmcnt(4)
	v_mov_b32_e32 v91, v116
	s_waitcnt vmcnt(3)
	v_or_b32_e32 v98, 48, v160
	v_pk_mul_f32 v[88:89], v[90:91], v[88:89]
	v_pk_mul_f32 v[90:91], v[90:91], v[84:85]
	v_pk_mul_f32 v[84:85], v[116:117], v[82:83]
	s_and_b64 vcc, exec, s[6:7]
	v_ashrrev_i32_e32 v99, 31, v98
	v_pk_mul_f32 v[86:87], v[116:117], v[86:87]
	s_nop 0
	v_cvt_pk_bf16_f32 v82, v86, v87
	v_cvt_pk_bf16_f32 v83, v88, v89
	v_cvt_pk_bf16_f32 v84, v84, v85
	v_cvt_pk_bf16_f32 v85, v90, v91
	v_subrev_u32_e32 v239, s14, v114
	global_store_dwordx4 v239, v[82:85], s[14:15] offset:256
	s_cbranch_vccnz .LBB0_127
	s_nop 0
	v_lshlrev_b64 v[82:83], 6, v[98:99]
	v_lshl_add_u64 v[90:91], s[16:17], 0, v[82:83]
	global_load_dwordx4 v[86:89], v[90:91], off
	global_load_dwordx4 v[82:85], v[90:91], off offset:16
	s_waitcnt lgkmcnt(1)
	global_load_dwordx4 v[94:97], v[90:91], off offset:32
	s_waitcnt lgkmcnt(0)
	global_load_dwordx4 v[90:93], v[90:91], off offset:48
	s_and_b64 vcc, exec, s[6:7]
	s_cbranch_vccz .LBB0_128
	s_branch .LBB0_131

; __device__ __forceinline__ unsigned cvt_pk_bf16(float lo, float hi) { unsigned r; asm volatile("v_cvt_pk_bf16_f32 %0, %1, %2" : "=v"(r) : "v"(lo), "v"(hi)); return r; }
;     __device__ __forceinline__ void operator()(const f32x4 (&acc)[2][2][4][2], const Unit& u, int wr, int wc, int fr, int fq, const float (&rsv)[8]) const {
;         const int row0 = u.pm * BM + wr * 64 + fr, col0 = u.pn * BM + wc * 32 + 8 * fq;
;         const bool isq = (u.pn < 2) || (u.pn == 6) || (u.pn == 7);
;         const float sc = isq ? QSCALE : 1.f;
;         const bool rotw = (u.pn < 4) && ((wc & 1) == 0);
;         const float sgn = (fq == 0) ? -1.f : 1.f; const bool rotl = fq < 2; const int pidx = (((fq ^ 1) << 4) | fr) << 2;
; #pragma unroll
;         for (int ai = 0; ai < 2; ++ai)
; #pragma unroll
;             for (int m = 0; m < 4; ++m) { const int row = row0 + ai * HALF + m * 16; bf16_t* rowp = O + (size_t)row * 3072 + col0; const float scr_ = sc * rsv[ai * 4 + m];
;                 f32x4 c0 = {1.f, 1.f, 1.f, 1.f}, c1 = c0, s0 = {0.f, 0.f, 0.f, 0.f}, s1 = s0;
;                 if (rotw) { const f32x4* rp = (const f32x4*)(rot + (size_t)row * 16); c0 = rp[0]; c1 = rp[1]; s0 = rp[2]; s1 = rp[3]; }
; #pragma unroll
;                 for (int bj = 0; bj < 2; ++bj) { f32x4 v0 = acc[ai][bj][m][0], v1 = acc[ai][bj][m][1];
;                     if (rotw) { f32x4 p0, p1;
; #pragma unroll
;                         for (int j = 0; j < 4; ++j) { const float a0 = v0[j], a1 = v1[j]; p0[j] = __int_as_float(__builtin_amdgcn_ds_bpermute(pidx, __float_as_int(a0))); p1[j] = __int_as_float(__builtin_amdgcn_ds_bpermute(pidx, __float_as_int(a1))); }
;                         if (rotl) { v0 = v0 * c0 + (p0 * s0) * sgn; v1 = v1 * c1 + (p1 * s1) * sgn; } }
;                     v0 = v0 * scr_; v1 = v1 * scr_; u32x4 w; w.x = cvt_pk_bf16(v0[0], v0[1]); w.y = cvt_pk_bf16(v0[2], v0[3]); w.z = cvt_pk_bf16(v1[0], v1[1]); w.w = cvt_pk_bf16(v1[2], v1[3]);
;                     *(u32x4*)(rowp + bj * HALF) = w; } }
.LBB0_131:
	s_waitcnt lgkmcnt(0)
	v_mov_b64_e32 v[102:103], s[14:15]
	v_mul_f32_e32 v100, v161, v179
	v_mad_i64_i32 v[98:99], s[42:43], v98, s97, v[102:103]
	v_lshl_add_u64 v[98:99], v[162:163], 1, v[98:99]
	v_pk_mul_f32 v[102:103], v[100:101], v[76:77] op_sel_hi:[0,1]
	v_pk_mul_f32 v[76:77], v[100:101], v[74:75] op_sel_hi:[0,1]
	s_and_b64 vcc, exec, s[6:7]
	v_pk_mul_f32 v[80:81], v[100:101], v[80:81] op_sel_hi:[0,1]
	v_pk_mul_f32 v[78:79], v[100:101], v[78:79] op_sel_hi:[0,1]
	v_cvt_pk_bf16_f32 v74, v78, v79
	v_cvt_pk_bf16_f32 v75, v80, v81
	v_cvt_pk_bf16_f32 v76, v76, v77
	v_cvt_pk_bf16_f32 v77, v102, v103
	v_subrev_u32_e32 v239, s14, v98
	global_store_dwordx4 v239, v[74:77], s[14:15]
	s_cbranch_vccnz .LBB0_135
	ds_bpermute_b32 v78, v173, v70
	ds_bpermute_b32 v74, v173, v66
	ds_bpermute_b32 v79, v173, v71
	ds_bpermute_b32 v75, v173, v67
	ds_bpermute_b32 v80, v173, v72
	ds_bpermute_b32 v76, v173, v68
	ds_bpermute_b32 v81, v173, v73
	ds_bpermute_b32 v77, v173, v69
	s_and_saveexec_b64 s[76:77], s[8:9]
	s_cbranch_execz .LBB0_134
	s_waitcnt vmcnt(2) lgkmcnt(1)
	v_pk_mul_f32 v[80:81], v[96:97], v[80:81]
	v_pk_mul_f32 v[78:79], v[94:95], v[78:79]
	s_waitcnt vmcnt(1) lgkmcnt(0)
	v_pk_mul_f32 v[76:77], v[92:93], v[76:77]
	v_pk_mul_f32 v[74:75], v[90:91], v[74:75]
	v_pk_mul_f32 v[80:81], v[154:155], v[80:81]
	v_pk_mul_f32 v[78:79], v[152:153], v[78:79]
	v_pk_mul_f32 v[76:77], v[154:155], v[76:77]
	v_pk_mul_f32 v[74:75], v[152:153], v[74:75]
	v_pk_fma_f32 v[72:73], v[72:73], v[88:89], v[80:81]
	v_pk_fma_f32 v[70:71], v[70:71], v[86:87], v[78:79]
	v_pk_fma_f32 v[68:69], v[68:69], v[84:85], v[76:77]
	v_pk_fma_f32 v[66:67], v[66:67], v[82:83], v[74:75]

; __device__ __forceinline__ unsigned cvt_pk_bf16(float lo, float hi) { unsigned r; asm volatile("v_cvt_pk_bf16_f32 %0, %1, %2" : "=v"(r) : "v"(lo), "v"(hi)); return r; }
;     __device__ __forceinline__ void operator()(const f32x4 (&acc)[2][2][4][2], const Unit& u, int wr, int wc, int fr, int fq, const float (&rsv)[8]) const {
;     ...
;             for (int m = 0; m < 4; ++m) { const int row = row0 + ai * HALF + m * 16; bf16_t* rowp = O + (size_t)row * 3072 + col0; const float scr_ = sc * rsv[ai * 4 + m];
;                 f32x4 c0 = {1.f, 1.f, 1.f, 1.f}, c1 = c0, s0 = {0.f, 0.f, 0.f, 0.f}, s1 = s0;
;                 if (rotw) { const f32x4* rp = (const f32x4*)(rot + (size_t)row * 16); c0 = rp[0]; c1 = rp[1]; s0 = rp[2]; s1 = rp[3]; }
; #pragma unroll
;                 for (int bj = 0; bj < 2; ++bj) { f32x4 v0 = acc[ai][bj][m][0], v1 = acc[ai][bj][m][1];
;                     if (rotw) { f32x4 p0, p1;
; #pragma unroll
;                         for (int j = 0; j < 4; ++j) { const float a0 = v0[j], a1 = v1[j]; p0[j] = __int_as_float(__builtin_amdgcn_ds_bpermute(pidx, __float_as_int(a0))); p1[j] = __int_as_float(__builtin_amdgcn_ds_bpermute(pidx, __float_as_int(a1))); }
;                         if (rotl) { v0 = v0 * c0 + (p0 * s0) * sgn; v1 = v1 * c1 + (p1 * s1) * sgn; } }
;                     v0 = v0 * scr_; v1 = v1 * scr_; u32x4 w; w.x = cvt_pk_bf16(v0[0], v0[1]); w.y = cvt_pk_bf16(v0[2], v0[3]); w.z = cvt_pk_bf16(v1[0], v1[1]); w.w = cvt_pk_bf16(v1[2], v1[3]);
;                     *(u32x4*)(rowp + bj * HALF) = w; } }
.LBB0_135:
	v_mov_b32_e32 v101, v100
	s_waitcnt vmcnt(3)
	v_add_u32_e32 v82, 0x80, v160
	s_waitcnt lgkmcnt(6)
	v_mov_b32_e32 v74, v100
	s_waitcnt lgkmcnt(4)
	v_mov_b32_e32 v75, v100
	v_ashrrev_i32_e32 v83, 31, v82
	v_pk_mul_f32 v[72:73], v[74:75], v[72:73]
	v_pk_mul_f32 v[74:75], v[74:75], v[68:69]
	v_pk_mul_f32 v[68:69], v[100:101], v[66:67]
	s_and_b64 vcc, exec, s[6:7]
	v_pk_mul_f32 v[70:71], v[100:101], v[70:71]
	s_nop 0
	v_cvt_pk_bf16_f32 v66, v70, v71
	v_cvt_pk_bf16_f32 v67, v72, v73
	v_cvt_pk_bf16_f32 v68, v68, v69
	v_cvt_pk_bf16_f32 v69, v74, v75
	v_subrev_u32_e32 v239, s14, v98
	global_store_dwordx4 v239, v[66:69], s[14:15] offset:256
	s_cbranch_vccnz .LBB0_137
	s_nop 0
	v_lshlrev_b64 v[66:67], 6, v[82:83]
	v_lshl_add_u64 v[74:75], s[16:17], 0, v[66:67]
	global_load_dwordx4 v[70:73], v[74:75], off
	global_load_dwordx4 v[66:69], v[74:75], off offset:16
	s_waitcnt lgkmcnt(1)
	global_load_dwordx4 v[78:81], v[74:75], off offset:32
	s_waitcnt lgkmcnt(0)
	global_load_dwordx4 v[74:77], v[74:75], off offset:48
	s_and_b64 vcc, exec, s[6:7]
	s_cbranch_vccz .LBB0_138
	s_branch .LBB0_141

; __device__ __forceinline__ unsigned cvt_pk_bf16(float lo, float hi) { unsigned r; asm volatile("v_cvt_pk_bf16_f32 %0, %1, %2" : "=v"(r) : "v"(lo), "v"(hi)); return r; }
;     __device__ __forceinline__ void operator()(const f32x4 (&acc)[2][2][4][2], const Unit& u, int wr, int wc, int fr, int fq, const float (&rsv)[8]) const {
;         const int row0 = u.pm * BM + wr * 64 + fr, col0 = u.pn * BM + wc * 32 + 8 * fq;
;         const bool isq = (u.pn < 2) || (u.pn == 6) || (u.pn == 7);
;         const float sc = isq ? QSCALE : 1.f;
;         const bool rotw = (u.pn < 4) && ((wc & 1) == 0);
;         const float sgn = (fq == 0) ? -1.f : 1.f; const bool rotl = fq < 2; const int pidx = (((fq ^ 1) << 4) | fr) << 2;
; #pragma unroll
;         for (int ai = 0; ai < 2; ++ai)
; #pragma unroll
;             for (int m = 0; m < 4; ++m) { const int row = row0 + ai * HALF + m * 16; bf16_t* rowp = O + (size_t)row * 3072 + col0; const float scr_ = sc * rsv[ai * 4 + m];
;                 f32x4 c0 = {1.f, 1.f, 1.f, 1.f}, c1 = c0, s0 = {0.f, 0.f, 0.f, 0.f}, s1 = s0;
;                 if (rotw) { const f32x4* rp = (const f32x4*)(rot + (size_t)row * 16); c0 = rp[0]; c1 = rp[1]; s0 = rp[2]; s1 = rp[3]; }
; #pragma unroll
;                 for (int bj = 0; bj < 2; ++bj) { f32x4 v0 = acc[ai][bj][m][0], v1 = acc[ai][bj][m][1];
;                     if (rotw) { f32x4 p0, p1;
; #pragma unroll
;                         for (int j = 0; j < 4; ++j) { const float a0 = v0[j], a1 = v1[j]; p0[j] = __int_as_float(__builtin_amdgcn_ds_bpermute(pidx, __float_as_int(a0))); p1[j] = __int_as_float(__builtin_amdgcn_ds_bpermute(pidx, __float_as_int(a1))); }
;                         if (rotl) { v0 = v0 * c0 + (p0 * s0) * sgn; v1 = v1 * c1 + (p1 * s1) * sgn; } }
;                     v0 = v0 * scr_; v1 = v1 * scr_; u32x4 w; w.x = cvt_pk_bf16(v0[0], v0[1]); w.y = cvt_pk_bf16(v0[2], v0[3]); w.z = cvt_pk_bf16(v1[0], v1[1]); w.w = cvt_pk_bf16(v1[2], v1[3]);
;                     *(u32x4*)(rowp + bj * HALF) = w; } }
.LBB0_141:
	s_waitcnt lgkmcnt(0)
	v_mov_b64_e32 v[86:87], s[14:15]
	v_mul_f32_e32 v84, v161, v178
	v_mad_i64_i32 v[82:83], s[42:43], v82, s97, v[86:87]
	v_lshl_add_u64 v[82:83], v[162:163], 1, v[82:83]
	v_pk_mul_f32 v[86:87], v[84:85], v[60:61] op_sel_hi:[0,1]
	v_pk_mul_f32 v[60:61], v[84:85], v[58:59] op_sel_hi:[0,1]
	s_and_b64 vcc, exec, s[6:7]
	v_pk_mul_f32 v[64:65], v[84:85], v[64:65] op_sel_hi:[0,1]
	v_pk_mul_f32 v[62:63], v[84:85], v[62:63] op_sel_hi:[0,1]
	v_cvt_pk_bf16_f32 v58, v62, v63
	v_cvt_pk_bf16_f32 v59, v64, v65
	v_cvt_pk_bf16_f32 v60, v60, v61
	v_cvt_pk_bf16_f32 v61, v86, v87
	v_subrev_u32_e32 v239, s14, v82
	global_store_dwordx4 v239, v[58:61], s[14:15]
	s_cbranch_vccnz .LBB0_145
	ds_bpermute_b32 v62, v173, v54
	ds_bpermute_b32 v58, v173, v50
	ds_bpermute_b32 v63, v173, v55
	ds_bpermute_b32 v59, v173, v51
	ds_bpermute_b32 v64, v173, v56
	ds_bpermute_b32 v60, v173, v52
	ds_bpermute_b32 v65, v173, v57
	ds_bpermute_b32 v61, v173, v53
	s_and_saveexec_b64 s[76:77], s[8:9]
	s_cbranch_execz .LBB0_144
	s_waitcnt vmcnt(2) lgkmcnt(1)
	v_pk_mul_f32 v[64:65], v[80:81], v[64:65]
	v_pk_mul_f32 v[62:63], v[78:79], v[62:63]
	s_waitcnt vmcnt(1) lgkmcnt(0)
	v_pk_mul_f32 v[60:61], v[76:77], v[60:61]
	v_pk_mul_f32 v[58:59], v[74:75], v[58:59]
	v_pk_mul_f32 v[64:65], v[154:155], v[64:65]
	v_pk_mul_f32 v[62:63], v[152:153], v[62:63]
	v_pk_mul_f32 v[60:61], v[154:155], v[60:61]
	v_pk_mul_f32 v[58:59], v[152:153], v[58:59]
	v_pk_fma_f32 v[56:57], v[56:57], v[72:73], v[64:65]
	v_pk_fma_f32 v[54:55], v[54:55], v[70:71], v[62:63]
	v_pk_fma_f32 v[52:53], v[52:53], v[68:69], v[60:61]
	v_pk_fma_f32 v[50:51], v[50:51], v[66:67], v[58:59]

; __device__ __forceinline__ unsigned cvt_pk_bf16(float lo, float hi) { unsigned r; asm volatile("v_cvt_pk_bf16_f32 %0, %1, %2" : "=v"(r) : "v"(lo), "v"(hi)); return r; }
;     __device__ __forceinline__ void operator()(const f32x4 (&acc)[2][2][4][2], const Unit& u, int wr, int wc, int fr, int fq, const float (&rsv)[8]) const {
;     ...
;             for (int m = 0; m < 4; ++m) { const int row = row0 + ai * HALF + m * 16; bf16_t* rowp = O + (size_t)row * 3072 + col0; const float scr_ = sc * rsv[ai * 4 + m];
;                 f32x4 c0 = {1.f, 1.f, 1.f, 1.f}, c1 = c0, s0 = {0.f, 0.f, 0.f, 0.f}, s1 = s0;
;                 if (rotw) { const f32x4* rp = (const f32x4*)(rot + (size_t)row * 16); c0 = rp[0]; c1 = rp[1]; s0 = rp[2]; s1 = rp[3]; }
; #pragma unroll
;                 for (int bj = 0; bj < 2; ++bj) { f32x4 v0 = acc[ai][bj][m][0], v1 = acc[ai][bj][m][1];
;                     if (rotw) { f32x4 p0, p1;
; #pragma unroll
;                         for (int j = 0; j < 4; ++j) { const float a0 = v0[j], a1 = v1[j]; p0[j] = __int_as_float(__builtin_amdgcn_ds_bpermute(pidx, __float_as_int(a0))); p1[j] = __int_as_float(__builtin_amdgcn_ds_bpermute(pidx, __float_as_int(a1))); }
;                         if (rotl) { v0 = v0 * c0 + (p0 * s0) * sgn; v1 = v1 * c1 + (p1 * s1) * sgn; } }
;                     v0 = v0 * scr_; v1 = v1 * scr_; u32x4 w; w.x = cvt_pk_bf16(v0[0], v0[1]); w.y = cvt_pk_bf16(v0[2], v0[3]); w.z = cvt_pk_bf16(v1[0], v1[1]); w.w = cvt_pk_bf16(v1[2], v1[3]);
;                     *(u32x4*)(rowp + bj * HALF) = w; } }
.LBB0_145:
	v_mov_b32_e32 v85, v84
	s_waitcnt lgkmcnt(6)
	v_mov_b32_e32 v58, v84
	s_waitcnt lgkmcnt(4)
	v_mov_b32_e32 v59, v84
	s_waitcnt vmcnt(3)
	v_add_u32_e32 v66, 0x90, v160
	v_pk_mul_f32 v[56:57], v[58:59], v[56:57]
	v_pk_mul_f32 v[58:59], v[58:59], v[52:53]
	v_pk_mul_f32 v[52:53], v[84:85], v[50:51]
	s_and_b64 vcc, exec, s[6:7]
	v_ashrrev_i32_e32 v67, 31, v66
	v_pk_mul_f32 v[54:55], v[84:85], v[54:55]
	s_nop 0
	v_cvt_pk_bf16_f32 v50, v54, v55
	v_cvt_pk_bf16_f32 v51, v56, v57
	v_cvt_pk_bf16_f32 v52, v52, v53
	v_cvt_pk_bf16_f32 v53, v58, v59
	v_subrev_u32_e32 v239, s14, v82
	global_store_dwordx4 v239, v[50:53], s[14:15] offset:256
	s_cbranch_vccnz .LBB0_147
	s_nop 0
	v_lshlrev_b64 v[50:51], 6, v[66:67]
	v_lshl_add_u64 v[58:59], s[16:17], 0, v[50:51]
	global_load_dwordx4 v[54:57], v[58:59], off
	global_load_dwordx4 v[50:53], v[58:59], off offset:16
	s_waitcnt lgkmcnt(1)
	global_load_dwordx4 v[62:65], v[58:59], off offset:32
	s_waitcnt lgkmcnt(0)
	global_load_dwordx4 v[58:61], v[58:59], off offset:48
	s_and_b64 vcc, exec, s[6:7]
	s_cbranch_vccz .LBB0_148
	s_branch .LBB0_151

; __device__ __forceinline__ unsigned cvt_pk_bf16(float lo, float hi) { unsigned r; asm volatile("v_cvt_pk_bf16_f32 %0, %1, %2" : "=v"(r) : "v"(lo), "v"(hi)); return r; }
;     __device__ __forceinline__ void operator()(const f32x4 (&acc)[2][2][4][2], const Unit& u, int wr, int wc, int fr, int fq, const float (&rsv)[8]) const {
;         const int row0 = u.pm * BM + wr * 64 + fr, col0 = u.pn * BM + wc * 32 + 8 * fq;
;         const bool isq = (u.pn < 2) || (u.pn == 6) || (u.pn == 7);
;         const float sc = isq ? QSCALE : 1.f;
;         const bool rotw = (u.pn < 4) && ((wc & 1) == 0);
;         const float sgn = (fq == 0) ? -1.f : 1.f; const bool rotl = fq < 2; const int pidx = (((fq ^ 1) << 4) | fr) << 2;
; #pragma unroll
;         for (int ai = 0; ai < 2; ++ai)
; #pragma unroll
;             for (int m = 0; m < 4; ++m) { const int row = row0 + ai * HALF + m * 16; bf16_t* rowp = O + (size_t)row * 3072 + col0; const float scr_ = sc * rsv[ai * 4 + m];
;                 f32x4 c0 = {1.f, 1.f, 1.f, 1.f}, c1 = c0, s0 = {0.f, 0.f, 0.f, 0.f}, s1 = s0;
;                 if (rotw) { const f32x4* rp = (const f32x4*)(rot + (size_t)row * 16); c0 = rp[0]; c1 = rp[1]; s0 = rp[2]; s1 = rp[3]; }
; #pragma unroll
;                 for (int bj = 0; bj < 2; ++bj) { f32x4 v0 = acc[ai][bj][m][0], v1 = acc[ai][bj][m][1];
;                     if (rotw) { f32x4 p0, p1;
; #pragma unroll
;                         for (int j = 0; j < 4; ++j) { const float a0 = v0[j], a1 = v1[j]; p0[j] = __int_as_float(__builtin_amdgcn_ds_bpermute(pidx, __float_as_int(a0))); p1[j] = __int_as_float(__builtin_amdgcn_ds_bpermute(pidx, __float_as_int(a1))); }
;                         if (rotl) { v0 = v0 * c0 + (p0 * s0) * sgn; v1 = v1 * c1 + (p1 * s1) * sgn; } }
;                     v0 = v0 * scr_; v1 = v1 * scr_; u32x4 w; w.x = cvt_pk_bf16(v0[0], v0[1]); w.y = cvt_pk_bf16(v0[2], v0[3]); w.z = cvt_pk_bf16(v1[0], v1[1]); w.w = cvt_pk_bf16(v1[2], v1[3]);
;                     *(u32x4*)(rowp + bj * HALF) = w; } }
.LBB0_151:
	s_waitcnt lgkmcnt(0)
	v_mov_b64_e32 v[70:71], s[14:15]
	v_mul_f32_e32 v68, v161, v177
	v_mad_i64_i32 v[66:67], s[42:43], v66, s97, v[70:71]
	v_lshl_add_u64 v[66:67], v[162:163], 1, v[66:67]
	v_pk_mul_f32 v[70:71], v[68:69], v[44:45] op_sel_hi:[0,1]
	v_pk_mul_f32 v[44:45], v[68:69], v[42:43] op_sel_hi:[0,1]
	s_and_b64 vcc, exec, s[6:7]
	v_pk_mul_f32 v[48:49], v[68:69], v[48:49] op_sel_hi:[0,1]
	v_pk_mul_f32 v[46:47], v[68:69], v[46:47] op_sel_hi:[0,1]
	v_cvt_pk_bf16_f32 v42, v46, v47
	v_cvt_pk_bf16_f32 v43, v48, v49
	v_cvt_pk_bf16_f32 v44, v44, v45
	v_cvt_pk_bf16_f32 v45, v70, v71
	v_subrev_u32_e32 v239, s14, v66
	global_store_dwordx4 v239, v[42:45], s[14:15]
	s_cbranch_vccnz .LBB0_155
	ds_bpermute_b32 v46, v173, v38
	ds_bpermute_b32 v42, v173, v34
	ds_bpermute_b32 v47, v173, v39
	ds_bpermute_b32 v43, v173, v35
	ds_bpermute_b32 v48, v173, v40
	ds_bpermute_b32 v44, v173, v36
	ds_bpermute_b32 v49, v173, v41
	ds_bpermute_b32 v45, v173, v37
	s_and_saveexec_b64 s[76:77], s[8:9]
	s_cbranch_execz .LBB0_154
	s_waitcnt vmcnt(2) lgkmcnt(1)
	v_pk_mul_f32 v[48:49], v[64:65], v[48:49]
	v_pk_mul_f32 v[46:47], v[62:63], v[46:47]
	s_waitcnt vmcnt(1) lgkmcnt(0)
	v_pk_mul_f32 v[44:45], v[60:61], v[44:45]
	v_pk_mul_f32 v[42:43], v[58:59], v[42:43]
	v_pk_mul_f32 v[48:49], v[154:155], v[48:49]
	v_pk_mul_f32 v[46:47], v[152:153], v[46:47]
	v_pk_mul_f32 v[44:45], v[154:155], v[44:45]
	v_pk_mul_f32 v[42:43], v[152:153], v[42:43]
	v_pk_fma_f32 v[40:41], v[40:41], v[56:57], v[48:49]
	v_pk_fma_f32 v[38:39], v[38:39], v[54:55], v[46:47]
	v_pk_fma_f32 v[36:37], v[36:37], v[52:53], v[44:45]
	v_pk_fma_f32 v[34:35], v[34:35], v[50:51], v[42:43]

; __device__ __forceinline__ unsigned cvt_pk_bf16(float lo, float hi) { unsigned r; asm volatile("v_cvt_pk_bf16_f32 %0, %1, %2" : "=v"(r) : "v"(lo), "v"(hi)); return r; }
;     __device__ __forceinline__ void operator()(const f32x4 (&acc)[2][2][4][2], const Unit& u, int wr, int wc, int fr, int fq, const float (&rsv)[8]) const {
;     ...
;             for (int m = 0; m < 4; ++m) { const int row = row0 + ai * HALF + m * 16; bf16_t* rowp = O + (size_t)row * 3072 + col0; const float scr_ = sc * rsv[ai * 4 + m];
;                 f32x4 c0 = {1.f, 1.f, 1.f, 1.f}, c1 = c0, s0 = {0.f, 0.f, 0.f, 0.f}, s1 = s0;
;                 if (rotw) { const f32x4* rp = (const f32x4*)(rot + (size_t)row * 16); c0 = rp[0]; c1 = rp[1]; s0 = rp[2]; s1 = rp[3]; }
; #pragma unroll
;                 for (int bj = 0; bj < 2; ++bj) { f32x4 v0 = acc[ai][bj][m][0], v1 = acc[ai][bj][m][1];
;                     if (rotw) { f32x4 p0, p1;
; #pragma unroll
;                         for (int j = 0; j < 4; ++j) { const float a0 = v0[j], a1 = v1[j]; p0[j] = __int_as_float(__builtin_amdgcn_ds_bpermute(pidx, __float_as_int(a0))); p1[j] = __int_as_float(__builtin_amdgcn_ds_bpermute(pidx, __float_as_int(a1))); }
;                         if (rotl) { v0 = v0 * c0 + (p0 * s0) * sgn; v1 = v1 * c1 + (p1 * s1) * sgn; } }
;                     v0 = v0 * scr_; v1 = v1 * scr_; u32x4 w; w.x = cvt_pk_bf16(v0[0], v0[1]); w.y = cvt_pk_bf16(v0[2], v0[3]); w.z = cvt_pk_bf16(v1[0], v1[1]); w.w = cvt_pk_bf16(v1[2], v1[3]);
;                     *(u32x4*)(rowp + bj * HALF) = w; } }
.LBB0_155:
	v_mov_b32_e32 v69, v68
	s_waitcnt lgkmcnt(6)
	v_mov_b32_e32 v42, v68
	s_waitcnt lgkmcnt(4)
	v_mov_b32_e32 v43, v68
	s_waitcnt vmcnt(3)
	v_add_u32_e32 v50, 0xa0, v160
	v_pk_mul_f32 v[40:41], v[42:43], v[40:41]
	v_pk_mul_f32 v[42:43], v[42:43], v[36:37]
	v_pk_mul_f32 v[36:37], v[68:69], v[34:35]
	s_and_b64 vcc, exec, s[6:7]
	v_ashrrev_i32_e32 v51, 31, v50
	v_pk_mul_f32 v[38:39], v[68:69], v[38:39]
	s_nop 0
	v_cvt_pk_bf16_f32 v34, v38, v39
	v_cvt_pk_bf16_f32 v35, v40, v41
	v_cvt_pk_bf16_f32 v36, v36, v37
	v_cvt_pk_bf16_f32 v37, v42, v43
	v_subrev_u32_e32 v239, s14, v66
	global_store_dwordx4 v239, v[34:37], s[14:15] offset:256
	s_cbranch_vccnz .LBB0_157
	s_nop 0
	v_lshlrev_b64 v[34:35], 6, v[50:51]
	v_lshl_add_u64 v[42:43], s[16:17], 0, v[34:35]
	global_load_dwordx4 v[38:41], v[42:43], off
	global_load_dwordx4 v[34:37], v[42:43], off offset:16
	s_waitcnt lgkmcnt(1)
	global_load_dwordx4 v[46:49], v[42:43], off offset:32
	s_waitcnt lgkmcnt(0)
	global_load_dwordx4 v[42:45], v[42:43], off offset:48
	s_and_b64 vcc, exec, s[6:7]
	s_cbranch_vccz .LBB0_158
	s_branch .LBB0_161

; __device__ __forceinline__ unsigned cvt_pk_bf16(float lo, float hi) { unsigned r; asm volatile("v_cvt_pk_bf16_f32 %0, %1, %2" : "=v"(r) : "v"(lo), "v"(hi)); return r; }
;     __device__ __forceinline__ void operator()(const f32x4 (&acc)[2][2][4][2], const Unit& u, int wr, int wc, int fr, int fq, const float (&rsv)[8]) const {
;         const int row0 = u.pm * BM + wr * 64 + fr, col0 = u.pn * BM + wc * 32 + 8 * fq;
;         const bool isq = (u.pn < 2) || (u.pn == 6) || (u.pn == 7);
;         const float sc = isq ? QSCALE : 1.f;
;         const bool rotw = (u.pn < 4) && ((wc & 1) == 0);
;         const float sgn = (fq == 0) ? -1.f : 1.f; const bool rotl = fq < 2; const int pidx = (((fq ^ 1) << 4) | fr) << 2;
; #pragma unroll
;         for (int ai = 0; ai < 2; ++ai)
; #pragma unroll
;             for (int m = 0; m < 4; ++m) { const int row = row0 + ai * HALF + m * 16; bf16_t* rowp = O + (size_t)row * 3072 + col0; const float scr_ = sc * rsv[ai * 4 + m];
;                 f32x4 c0 = {1.f, 1.f, 1.f, 1.f}, c1 = c0, s0 = {0.f, 0.f, 0.f, 0.f}, s1 = s0;
;                 if (rotw) { const f32x4* rp = (const f32x4*)(rot + (size_t)row * 16); c0 = rp[0]; c1 = rp[1]; s0 = rp[2]; s1 = rp[3]; }
; #pragma unroll
;                 for (int bj = 0; bj < 2; ++bj) { f32x4 v0 = acc[ai][bj][m][0], v1 = acc[ai][bj][m][1];
;                     if (rotw) { f32x4 p0, p1;
; #pragma unroll
;                         for (int j = 0; j < 4; ++j) { const float a0 = v0[j], a1 = v1[j]; p0[j] = __int_as_float(__builtin_amdgcn_ds_bpermute(pidx, __float_as_int(a0))); p1[j] = __int_as_float(__builtin_amdgcn_ds_bpermute(pidx, __float_as_int(a1))); }
;                         if (rotl) { v0 = v0 * c0 + (p0 * s0) * sgn; v1 = v1 * c1 + (p1 * s1) * sgn; } }
;                     v0 = v0 * scr_; v1 = v1 * scr_; u32x4 w; w.x = cvt_pk_bf16(v0[0], v0[1]); w.y = cvt_pk_bf16(v0[2], v0[3]); w.z = cvt_pk_bf16(v1[0], v1[1]); w.w = cvt_pk_bf16(v1[2], v1[3]);
;                     *(u32x4*)(rowp + bj * HALF) = w; } }
.LBB0_161:
	s_waitcnt lgkmcnt(0)
	v_mov_b64_e32 v[54:55], s[14:15]
	v_mul_f32_e32 v52, v161, v176
	v_mad_i64_i32 v[50:51], s[42:43], v50, s97, v[54:55]
	v_lshl_add_u64 v[50:51], v[162:163], 1, v[50:51]
	v_pk_mul_f32 v[54:55], v[52:53], v[28:29] op_sel_hi:[0,1]
	v_pk_mul_f32 v[28:29], v[52:53], v[26:27] op_sel_hi:[0,1]
	s_and_b64 vcc, exec, s[6:7]
	v_pk_mul_f32 v[32:33], v[52:53], v[32:33] op_sel_hi:[0,1]
	v_pk_mul_f32 v[30:31], v[52:53], v[30:31] op_sel_hi:[0,1]
	v_cvt_pk_bf16_f32 v26, v30, v31
	v_cvt_pk_bf16_f32 v27, v32, v33
	v_cvt_pk_bf16_f32 v28, v28, v29
	v_cvt_pk_bf16_f32 v29, v54, v55
	v_subrev_u32_e32 v239, s14, v50
	global_store_dwordx4 v239, v[26:29], s[14:15]
	s_cbranch_vccnz .LBB0_165
	ds_bpermute_b32 v30, v173, v22
	ds_bpermute_b32 v26, v173, v18
	ds_bpermute_b32 v31, v173, v23
	ds_bpermute_b32 v27, v173, v19
	ds_bpermute_b32 v32, v173, v24
	ds_bpermute_b32 v28, v173, v20
	ds_bpermute_b32 v33, v173, v25
	ds_bpermute_b32 v29, v173, v21
	s_and_saveexec_b64 s[76:77], s[8:9]
	s_cbranch_execz .LBB0_164
	s_waitcnt vmcnt(2) lgkmcnt(1)
	v_pk_mul_f32 v[32:33], v[48:49], v[32:33]
	v_pk_mul_f32 v[30:31], v[46:47], v[30:31]
	s_waitcnt vmcnt(1) lgkmcnt(0)
	v_pk_mul_f32 v[28:29], v[44:45], v[28:29]
	v_pk_mul_f32 v[26:27], v[42:43], v[26:27]
	v_pk_mul_f32 v[32:33], v[154:155], v[32:33]
	v_pk_mul_f32 v[30:31], v[152:153], v[30:31]
	v_pk_mul_f32 v[28:29], v[154:155], v[28:29]
	v_pk_mul_f32 v[26:27], v[152:153], v[26:27]
	v_pk_fma_f32 v[24:25], v[24:25], v[40:41], v[32:33]
	v_pk_fma_f32 v[22:23], v[22:23], v[38:39], v[30:31]
	v_pk_fma_f32 v[20:21], v[20:21], v[36:37], v[28:29]
	v_pk_fma_f32 v[18:19], v[18:19], v[34:35], v[26:27]

; __device__ __forceinline__ unsigned cvt_pk_bf16(float lo, float hi) { unsigned r; asm volatile("v_cvt_pk_bf16_f32 %0, %1, %2" : "=v"(r) : "v"(lo), "v"(hi)); return r; }
;     __device__ __forceinline__ void operator()(const f32x4 (&acc)[2][2][4][2], const Unit& u, int wr, int wc, int fr, int fq, const float (&rsv)[8]) const {
;     ...
;             for (int m = 0; m < 4; ++m) { const int row = row0 + ai * HALF + m * 16; bf16_t* rowp = O + (size_t)row * 3072 + col0; const float scr_ = sc * rsv[ai * 4 + m];
;                 f32x4 c0 = {1.f, 1.f, 1.f, 1.f}, c1 = c0, s0 = {0.f, 0.f, 0.f, 0.f}, s1 = s0;
;                 if (rotw) { const f32x4* rp = (const f32x4*)(rot + (size_t)row * 16); c0 = rp[0]; c1 = rp[1]; s0 = rp[2]; s1 = rp[3]; }
; #pragma unroll
;                 for (int bj = 0; bj < 2; ++bj) { f32x4 v0 = acc[ai][bj][m][0], v1 = acc[ai][bj][m][1];
;                     if (rotw) { f32x4 p0, p1;
; #pragma unroll
;                         for (int j = 0; j < 4; ++j) { const float a0 = v0[j], a1 = v1[j]; p0[j] = __int_as_float(__builtin_amdgcn_ds_bpermute(pidx, __float_as_int(a0))); p1[j] = __int_as_float(__builtin_amdgcn_ds_bpermute(pidx, __float_as_int(a1))); }
;                         if (rotl) { v0 = v0 * c0 + (p0 * s0) * sgn; v1 = v1 * c1 + (p1 * s1) * sgn; } }
;                     v0 = v0 * scr_; v1 = v1 * scr_; u32x4 w; w.x = cvt_pk_bf16(v0[0], v0[1]); w.y = cvt_pk_bf16(v0[2], v0[3]); w.z = cvt_pk_bf16(v1[0], v1[1]); w.w = cvt_pk_bf16(v1[2], v1[3]);
;                     *(u32x4*)(rowp + bj * HALF) = w; } }
.LBB0_165:
	v_mov_b32_e32 v53, v52
	s_waitcnt lgkmcnt(6)
	v_mov_b32_e32 v26, v52
	s_waitcnt lgkmcnt(4)
	v_mov_b32_e32 v27, v52
	s_waitcnt vmcnt(3)
	v_add_u32_e32 v34, 0xb0, v160
	v_pk_mul_f32 v[24:25], v[26:27], v[24:25]
	v_pk_mul_f32 v[26:27], v[26:27], v[20:21]
	v_pk_mul_f32 v[20:21], v[52:53], v[18:19]
	s_and_b64 vcc, exec, s[6:7]
	v_ashrrev_i32_e32 v35, 31, v34
	v_pk_mul_f32 v[22:23], v[52:53], v[22:23]
	s_nop 0
	v_cvt_pk_bf16_f32 v18, v22, v23
	v_cvt_pk_bf16_f32 v19, v24, v25
	v_cvt_pk_bf16_f32 v20, v20, v21
	v_cvt_pk_bf16_f32 v21, v26, v27
	v_subrev_u32_e32 v239, s14, v50
	global_store_dwordx4 v239, v[18:21], s[14:15] offset:256
	s_cbranch_vccnz .LBB0_167
	s_nop 0
	v_lshlrev_b64 v[18:19], 6, v[34:35]
	v_lshl_add_u64 v[26:27], s[16:17], 0, v[18:19]
	global_load_dwordx4 v[22:25], v[26:27], off
	global_load_dwordx4 v[18:21], v[26:27], off offset:16
	s_waitcnt lgkmcnt(1)
	global_load_dwordx4 v[30:33], v[26:27], off offset:32
	s_waitcnt lgkmcnt(0)
	global_load_dwordx4 v[26:29], v[26:27], off offset:48
	s_and_b64 vcc, exec, s[6:7]
	s_cbranch_vccz .LBB0_168
	s_branch .LBB0_171

; __device__ __forceinline__ unsigned cvt_pk_bf16(float lo, float hi) { unsigned r; asm volatile("v_cvt_pk_bf16_f32 %0, %1, %2" : "=v"(r) : "v"(lo), "v"(hi)); return r; }
;     __device__ __forceinline__ void operator()(const f32x4 (&acc)[2][2][4][2], const Unit& u, int wr, int wc, int fr, int fq, const float (&rsv)[8]) const {
;         const int row0 = u.pm * BM + wr * 64 + fr, col0 = u.pn * BM + wc * 32 + 8 * fq;
;         const bool isq = (u.pn < 2) || (u.pn == 6) || (u.pn == 7);
;         const float sc = isq ? QSCALE : 1.f;
;         const bool rotw = (u.pn < 4) && ((wc & 1) == 0);
;         const float sgn = (fq == 0) ? -1.f : 1.f; const bool rotl = fq < 2; const int pidx = (((fq ^ 1) << 4) | fr) << 2;
; #pragma unroll
;         for (int ai = 0; ai < 2; ++ai)
; #pragma unroll
;             for (int m = 0; m < 4; ++m) { const int row = row0 + ai * HALF + m * 16; bf16_t* rowp = O + (size_t)row * 3072 + col0; const float scr_ = sc * rsv[ai * 4 + m];
;                 f32x4 c0 = {1.f, 1.f, 1.f, 1.f}, c1 = c0, s0 = {0.f, 0.f, 0.f, 0.f}, s1 = s0;
;                 if (rotw) { const f32x4* rp = (const f32x4*)(rot + (size_t)row * 16); c0 = rp[0]; c1 = rp[1]; s0 = rp[2]; s1 = rp[3]; }
; #pragma unroll
;                 for (int bj = 0; bj < 2; ++bj) { f32x4 v0 = acc[ai][bj][m][0], v1 = acc[ai][bj][m][1];
;                     if (rotw) { f32x4 p0, p1;
; #pragma unroll
;                         for (int j = 0; j < 4; ++j) { const float a0 = v0[j], a1 = v1[j]; p0[j] = __int_as_float(__builtin_amdgcn_ds_bpermute(pidx, __float_as_int(a0))); p1[j] = __int_as_float(__builtin_amdgcn_ds_bpermute(pidx, __float_as_int(a1))); }
;                         if (rotl) { v0 = v0 * c0 + (p0 * s0) * sgn; v1 = v1 * c1 + (p1 * s1) * sgn; } }
;                     v0 = v0 * scr_; v1 = v1 * scr_; u32x4 w; w.x = cvt_pk_bf16(v0[0], v0[1]); w.y = cvt_pk_bf16(v0[2], v0[3]); w.z = cvt_pk_bf16(v1[0], v1[1]); w.w = cvt_pk_bf16(v1[2], v1[3]);
;                     *(u32x4*)(rowp + bj * HALF) = w; } }
.LBB0_171:
	s_waitcnt lgkmcnt(0)
	v_mov_b64_e32 v[38:39], s[14:15]
	v_mul_f32_e32 v36, v161, v175
	v_mad_i64_i32 v[34:35], s[42:43], v34, s97, v[38:39]
	v_lshl_add_u64 v[34:35], v[162:163], 1, v[34:35]
	v_pk_mul_f32 v[38:39], v[36:37], v[12:13] op_sel_hi:[0,1]
	v_pk_mul_f32 v[12:13], v[36:37], v[10:11] op_sel_hi:[0,1]
	s_and_b64 vcc, exec, s[6:7]
	v_pk_mul_f32 v[16:17], v[36:37], v[16:17] op_sel_hi:[0,1]
	v_pk_mul_f32 v[14:15], v[36:37], v[14:15] op_sel_hi:[0,1]
	v_cvt_pk_bf16_f32 v10, v14, v15
	v_cvt_pk_bf16_f32 v11, v16, v17
	v_cvt_pk_bf16_f32 v12, v12, v13
	v_cvt_pk_bf16_f32 v13, v38, v39
	v_subrev_u32_e32 v239, s14, v34
	global_store_dwordx4 v239, v[10:13], s[14:15]
	s_cbranch_vccnz .LBB0_175
	ds_bpermute_b32 v14, v173, v6
	ds_bpermute_b32 v10, v173, v2
	ds_bpermute_b32 v15, v173, v7
	ds_bpermute_b32 v11, v173, v3
	ds_bpermute_b32 v16, v173, v8
	ds_bpermute_b32 v12, v173, v4
	ds_bpermute_b32 v17, v173, v9
	ds_bpermute_b32 v13, v173, v5
	s_and_saveexec_b64 s[6:7], s[8:9]
	s_cbranch_execz .LBB0_174
	s_waitcnt vmcnt(2) lgkmcnt(1)
	v_pk_mul_f32 v[16:17], v[32:33], v[16:17]
	v_pk_mul_f32 v[14:15], v[30:31], v[14:15]
	s_waitcnt vmcnt(1) lgkmcnt(0)
	v_pk_mul_f32 v[12:13], v[28:29], v[12:13]
	v_pk_mul_f32 v[10:11], v[26:27], v[10:11]
	v_pk_mul_f32 v[16:17], v[154:155], v[16:17]
	v_pk_mul_f32 v[14:15], v[152:153], v[14:15]
	v_pk_mul_f32 v[12:13], v[154:155], v[12:13]
	v_pk_mul_f32 v[10:11], v[152:153], v[10:11]
	v_pk_fma_f32 v[8:9], v[8:9], v[24:25], v[16:17]
	v_pk_fma_f32 v[6:7], v[6:7], v[22:23], v[14:15]
	v_pk_fma_f32 v[4:5], v[4:5], v[20:21], v[12:13]
	v_pk_fma_f32 v[2:3], v[2:3], v[18:19], v[10:11]

; __device__ __forceinline__ unsigned cvt_pk_bf16(float lo, float hi) { unsigned r; asm volatile("v_cvt_pk_bf16_f32 %0, %1, %2" : "=v"(r) : "v"(lo), "v"(hi)); return r; }
; #define PG8_BAR __builtin_amdgcn_s_barrier()
;     __device__ __forceinline__ void operator()(const f32x4 (&acc)[2][2][4][2], const Unit& u, int wr, int wc, int fr, int fq, const float (&rsv)[8]) const {
;     ...
;             for (int m = 0; m < 4; ++m) { const int row = row0 + ai * HALF + m * 16; bf16_t* rowp = O + (size_t)row * 3072 + col0; const float scr_ = sc * rsv[ai * 4 + m];
;                 f32x4 c0 = {1.f, 1.f, 1.f, 1.f}, c1 = c0, s0 = {0.f, 0.f, 0.f, 0.f}, s1 = s0;
;                 if (rotw) { const f32x4* rp = (const f32x4*)(rot + (size_t)row * 16); c0 = rp[0]; c1 = rp[1]; s0 = rp[2]; s1 = rp[3]; }
; #pragma unroll
;                 for (int bj = 0; bj < 2; ++bj) { f32x4 v0 = acc[ai][bj][m][0], v1 = acc[ai][bj][m][1];
;                     if (rotw) { f32x4 p0, p1;
; #pragma unroll
;                         for (int j = 0; j < 4; ++j) { const float a0 = v0[j], a1 = v1[j]; p0[j] = __int_as_float(__builtin_amdgcn_ds_bpermute(pidx, __float_as_int(a0))); p1[j] = __int_as_float(__builtin_amdgcn_ds_bpermute(pidx, __float_as_int(a1))); }
;                         if (rotl) { v0 = v0 * c0 + (p0 * s0) * sgn; v1 = v1 * c1 + (p1 * s1) * sgn; } }
;                     v0 = v0 * scr_; v1 = v1 * scr_; u32x4 w; w.x = cvt_pk_bf16(v0[0], v0[1]); w.y = cvt_pk_bf16(v0[2], v0[3]); w.z = cvt_pk_bf16(v1[0], v1[1]); w.w = cvt_pk_bf16(v1[2], v1[3]);
;                     *(u32x4*)(rowp + bj * HALF) = w; } }
; template <class Epi, class Sched, bool ALIGN_EPI = false, bool SP2 = false>
; __device__ __forceinline__ void gemm_phase(PG8_LAS unsigned char* lds, const Gemm g, const Sched& S, const Epi& E, const int tid_in) {
;     ...
;         if (!has_next) break;
; #pragma unroll
;         for (int a = 0; a < 2; ++a)
; #pragma unroll
;             for (int b = 0; b < 2; ++b)
; #pragma unroll
;                 for (int m = 0; m < 4; ++m)
; #pragma unroll
;                     for (int n = 0; n < 2; ++n) acc[a][b][m][n] = (f32x4){0.f, 0.f, 0.f, 0.f};
;         cur = nxt; cA = nA; cB = nB; ++ui;
;         if constexpr (ALIGN_EPI) { if (wr == 1) PG8_BAR; }
.LBB0_175:
	v_mov_b32_e32 v37, v36
	s_waitcnt lgkmcnt(6)
	v_mov_b32_e32 v10, v36
	s_waitcnt lgkmcnt(4)
	v_mov_b32_e32 v11, v36
	v_pk_mul_f32 v[8:9], v[10:11], v[8:9]
	v_pk_mul_f32 v[10:11], v[10:11], v[4:5]
	v_pk_mul_f32 v[4:5], v[36:37], v[2:3]
	s_andn2_b64 vcc, exec, s[4:5]
	s_mov_b64 s[4:5], -1
	v_pk_mul_f32 v[6:7], v[36:37], v[6:7]
	s_nop 0
	v_cvt_pk_bf16_f32 v2, v6, v7
	v_cvt_pk_bf16_f32 v3, v8, v9
	v_cvt_pk_bf16_f32 v4, v4, v5
	v_cvt_pk_bf16_f32 v5, v10, v11
	v_subrev_u32_e32 v239, s14, v34
	global_store_dwordx4 v239, v[2:5], s[14:15] offset:256
	s_cbranch_vccnz .LBB0_88
	s_andn2_b64 vcc, exec, s[12:13]
	s_cbranch_vccnz .LBB0_87
	s_barrier
	s_branch .LBB0_87

; __device__ __forceinline__ unsigned cvt_pk_bf16(float lo, float hi) { unsigned r; asm volatile("v_cvt_pk_bf16_f32 %0, %1, %2" : "=v"(r) : "v"(lo), "v"(hi)); return r; }
; #define PG8_BAR __builtin_amdgcn_s_barrier()
;     __device__ __forceinline__ void operator()(const f32x4 (&acc)[2][2][4][2], const Unit& u, int wr, int wc, int fr, int fq, const float (&rsv)[8]) const {
;         const int row0 = u.pm * BM + wr * 64 + fr, col0 = u.pn * BM + wc * 32 + 8 * fq;
; #pragma unroll
;         for (int ai = 0; ai < 2; ++ai)
; #pragma unroll
;             for (int m = 0; m < 4; ++m) { bf16_t* rowp = O + (size_t)(row0 + ai * HALF + m * 16) * ldc + col0;
; #pragma unroll
;                 for (int bj = 0; bj < 2; ++bj) { const f32x4 v0 = acc[ai][bj][m][0], v1 = acc[ai][bj][m][1];
;                     u32x4 w; w.x = cvt_pk_bf16(v0[0], v0[1]); w.y = cvt_pk_bf16(v0[2], v0[3]); w.z = cvt_pk_bf16(v1[0], v1[1]); w.w = cvt_pk_bf16(v1[2], v1[3]);
;                     *(u32x4*)(rowp + bj * HALF) = w; } }
;     }
; template <class Epi, class Sched, bool ALIGN_EPI = false, bool SP2 = false>
; __device__ __forceinline__ void gemm_phase(PG8_LAS unsigned char* lds, const Gemm g, const Sched& S, const Epi& E, const int tid_in) {
;     ...
;         if (!has_next) break;
; #pragma unroll
;         for (int a = 0; a < 2; ++a)
; #pragma unroll
;             for (int b = 0; b < 2; ++b)
; #pragma unroll
;                 for (int m = 0; m < 4; ++m)
; #pragma unroll
;                     for (int n = 0; n < 2; ++n) acc[a][b][m][n] = (f32x4){0.f, 0.f, 0.f, 0.f};
;         cur = nxt; cA = nA; cB = nB; ++ui;
;         if constexpr (ALIGN_EPI) { if (wr == 1) PG8_BAR; }
.LBB0_488:
	v_lshl_add_u32 v146, s16, 8, v142
	v_lshl_or_b32 v140, s38, 8, v144
	v_ashrrev_i32_e32 v147, 31, v146
	v_ashrrev_i32_e32 v141, 31, v140
	v_lshlrev_b64 v[148:149], 11, v[146:147]
	v_lshl_add_u64 v[148:149], s[8:9], 0, v[148:149]
	v_lshlrev_b64 v[150:151], 1, v[140:141]
	v_lshl_add_u64 v[140:141], v[148:149], 0, v[150:151]
	v_cvt_pk_bf16_f32 v126, v126, v127
	v_cvt_pk_bf16_f32 v127, v128, v129
	v_cvt_pk_bf16_f32 v128, v122, v123
	v_cvt_pk_bf16_f32 v129, v124, v125
	v_subrev_u32_e32 v218, s8, v140
	global_store_dwordx4 v218, v[126:129], s[8:9]
	v_cvt_pk_bf16_f32 v114, v114, v115
	v_cvt_pk_bf16_f32 v115, v116, v117
	v_cvt_pk_bf16_f32 v116, v106, v107
	v_or_b32_e32 v106, 16, v146
	v_ashrrev_i32_e32 v107, 31, v106
	v_lshlrev_b64 v[106:107], 11, v[106:107]
	v_lshl_add_u64 v[106:107], s[8:9], 0, v[106:107]
	v_cvt_pk_bf16_f32 v117, v108, v109
	v_subrev_u32_e32 v218, s8, v140
	global_store_dwordx4 v218, v[114:117], s[8:9] offset:256
	s_nop 1
	v_lshl_add_u64 v[114:115], v[106:107], 0, v[150:151]
	v_cvt_pk_bf16_f32 v106, v118, v119
	v_cvt_pk_bf16_f32 v107, v120, v121
	v_cvt_pk_bf16_f32 v108, v110, v111
	v_cvt_pk_bf16_f32 v109, v112, v113
	v_subrev_u32_e32 v218, s8, v114
	global_store_dwordx4 v218, v[106:109], s[8:9]
	v_cvt_pk_bf16_f32 v98, v98, v99
	v_cvt_pk_bf16_f32 v99, v100, v101
	v_cvt_pk_bf16_f32 v100, v90, v91
	v_or_b32_e32 v90, 32, v146
	v_ashrrev_i32_e32 v91, 31, v90
	v_lshlrev_b64 v[90:91], 11, v[90:91]
	v_lshl_add_u64 v[90:91], s[8:9], 0, v[90:91]
	v_cvt_pk_bf16_f32 v101, v92, v93
	v_subrev_u32_e32 v218, s8, v114
	global_store_dwordx4 v218, v[98:101], s[8:9] offset:256
	s_nop 1
	v_lshl_add_u64 v[98:99], v[90:91], 0, v[150:151]
	v_cvt_pk_bf16_f32 v90, v102, v103
	v_cvt_pk_bf16_f32 v91, v104, v105
	v_cvt_pk_bf16_f32 v92, v94, v95
	v_cvt_pk_bf16_f32 v93, v96, v97
	v_subrev_u32_e32 v218, s8, v98
	global_store_dwordx4 v218, v[90:93], s[8:9]
	v_cvt_pk_bf16_f32 v82, v82, v83
	v_cvt_pk_bf16_f32 v83, v84, v85
	v_cvt_pk_bf16_f32 v84, v74, v75
	v_or_b32_e32 v74, 48, v146
	v_ashrrev_i32_e32 v75, 31, v74
	v_lshlrev_b64 v[74:75], 11, v[74:75]
	v_lshl_add_u64 v[74:75], s[8:9], 0, v[74:75]
	v_cvt_pk_bf16_f32 v85, v76, v77
	v_subrev_u32_e32 v218, s8, v98
	global_store_dwordx4 v218, v[82:85], s[8:9] offset:256
	s_nop 1
	v_lshl_add_u64 v[82:83], v[74:75], 0, v[150:151]
	v_cvt_pk_bf16_f32 v74, v86, v87
	v_cvt_pk_bf16_f32 v75, v88, v89
	v_cvt_pk_bf16_f32 v76, v78, v79
	v_cvt_pk_bf16_f32 v77, v80, v81
	v_subrev_u32_e32 v218, s8, v82
	global_store_dwordx4 v218, v[74:77], s[8:9]
	v_cvt_pk_bf16_f32 v70, v70, v71
	v_cvt_pk_bf16_f32 v71, v72, v73
	v_cvt_pk_bf16_f32 v72, v66, v67
	v_cvt_pk_bf16_f32 v73, v68, v69
	v_subrev_u32_e32 v218, s8, v82
	global_store_dwordx4 v218, v[70:73], s[8:9] offset:256
	v_cvt_pk_bf16_f32 v62, v62, v63
	v_cvt_pk_bf16_f32 v63, v64, v65
	v_cvt_pk_bf16_f32 v64, v58, v59
	v_add_co_u32_e32 v58, vcc, s77, v140
	v_lshl_add_u64 v[66:67], v[140:141], 0, s[80:81]
	s_nop 0
	v_addc_co_u32_e32 v59, vcc, 0, v141, vcc
	v_cvt_pk_bf16_f32 v65, v60, v61
	v_subrev_u32_e32 v218, s8, v58
	global_store_dwordx4 v218, v[62:65], s[8:9]
	v_cvt_pk_bf16_f32 v50, v50, v51
	v_cvt_pk_bf16_f32 v51, v52, v53
	v_cvt_pk_bf16_f32 v52, v42, v43
	v_cvt_pk_bf16_f32 v53, v44, v45
	v_subrev_u32_e32 v218, s8, v66
	global_store_dwordx4 v218, v[50:53], s[8:9] offset:256
	v_cvt_pk_bf16_f32 v42, v54, v55
	v_cvt_pk_bf16_f32 v43, v56, v57
	v_cvt_pk_bf16_f32 v44, v46, v47
	v_add_co_u32_e32 v46, vcc, s87, v140
	s_nop 0
	v_lshl_add_u64 v[50:51], v[140:141], 0, s[88:89]
	v_addc_co_u32_e32 v47, vcc, 0, v141, vcc
	v_cvt_pk_bf16_f32 v45, v48, v49
	v_subrev_u32_e32 v218, s8, v46
	global_store_dwordx4 v218, v[42:45], s[8:9]
	v_cvt_pk_bf16_f32 v34, v34, v35
	v_cvt_pk_bf16_f32 v35, v36, v37
	v_cvt_pk_bf16_f32 v36, v26, v27
	v_cvt_pk_bf16_f32 v37, v28, v29
	v_subrev_u32_e32 v218, s8, v50
	global_store_dwordx4 v218, v[34:37], s[8:9] offset:256
	v_cvt_pk_bf16_f32 v26, v38, v39
	v_cvt_pk_bf16_f32 v27, v40, v41
	v_cvt_pk_bf16_f32 v28, v30, v31
	v_add_co_u32_e32 v30, vcc, s94, v140
	s_nop 0
	v_lshl_add_u64 v[34:35], v[140:141], 0, s[90:91]
	v_addc_co_u32_e32 v31, vcc, 0, v141, vcc
	v_cvt_pk_bf16_f32 v29, v32, v33
	v_subrev_u32_e32 v218, s8, v30
	global_store_dwordx4 v218, v[26:29], s[8:9]
	v_cvt_pk_bf16_f32 v18, v18, v19
	v_cvt_pk_bf16_f32 v19, v20, v21
	v_cvt_pk_bf16_f32 v20, v10, v11
	v_cvt_pk_bf16_f32 v21, v12, v13
	v_subrev_u32_e32 v218, s8, v34
	global_store_dwordx4 v218, v[18:21], s[8:9] offset:256
	v_cvt_pk_bf16_f32 v10, v22, v23
	v_cvt_pk_bf16_f32 v11, v24, v25
	v_cvt_pk_bf16_f32 v12, v14, v15
	v_add_co_u32_e32 v14, vcc, s95, v140
	s_nop 0
	v_lshl_add_u64 v[18:19], v[140:141], 0, s[92:93]
	v_addc_co_u32_e32 v15, vcc, 0, v141, vcc
	s_andn2_b64 vcc, exec, s[4:5]
	s_mov_b64 s[4:5], -1
	v_cvt_pk_bf16_f32 v13, v16, v17
	v_subrev_u32_e32 v218, s8, v14
	global_store_dwordx4 v218, v[10:13], s[8:9]
	v_cvt_pk_bf16_f32 v6, v6, v7
	v_cvt_pk_bf16_f32 v7, v8, v9
	v_cvt_pk_bf16_f32 v8, v2, v3
	v_cvt_pk_bf16_f32 v9, v4, v5
	v_subrev_u32_e32 v218, s8, v18
	global_store_dwordx4 v218, v[6:9], s[8:9] offset:256
	s_cbranch_vccnz .LBB0_477
	s_andn2_b64 vcc, exec, s[6:7]
	s_cbranch_vccnz .LBB0_476
	s_barrier
	s_branch .LBB0_476

; __device__ __forceinline__ unsigned cvt_pk_bf16(float lo, float hi) { unsigned r; asm volatile("v_cvt_pk_bf16_f32 %0, %1, %2" : "=v"(r) : "v"(lo), "v"(hi)); return r; }
;     __device__ __forceinline__ void operator()(const f32x4 (&acc)[2][2][4][2], const Unit& u, int wr, int wc, int fr, int fq, const float (&rsv)[8]) const {
;         const int row0 = u.pm * BM + wr * 64 + fr, col0 = u.pn * HALF + wc * 32 + 8 * fq;
; #pragma unroll
;         for (int ai = 0; ai < 2; ++ai)
; #pragma unroll
;             for (int m = 0; m < 4; ++m) { bf16_t* rowp = O + (size_t)(row0 + ai * HALF + m * 16) * ldc + col0; float r[8]; const float rr = rsv[ai * 4 + m];
; #pragma unroll
;                 for (int n = 0; n < 2; ++n)
; #pragma unroll
;                     for (int j = 0; j < 4; ++j) { const float g = acc[ai][0][m][n][j] * rr, up = acc[ai][1][m][n][j] * rr;
;                         const float e = __builtin_amdgcn_exp2f(g * -1.4426950408889634f); r[n * 4 + j] = g * __builtin_amdgcn_rcpf(1.0f + e) * up; }
;                 u32x4 w; w.x = cvt_pk_bf16(r[0], r[1]); w.y = cvt_pk_bf16(r[2], r[3]); w.z = cvt_pk_bf16(r[4], r[5]); w.w = cvt_pk_bf16(r[6], r[7]);
;                 *(u32x4*)rowp = w; }
.LBB0_625:
	v_mov_b32_e32 v164, v126
	v_mov_b32_e32 v165, v122
	s_waitcnt vmcnt(8)
	v_pk_mul_f32 v[164:165], v[158:159], v[164:165] op_sel_hi:[0,1]
	v_mul_f32_e32 v122, 0xbfb8aa3b, v164
	v_exp_f32_e32 v122, v122
	v_lshl_or_b32 v160, s42, 7, v147
	v_ashrrev_i32_e32 v161, 31, v160
	v_mov_b64_e32 v[154:155], s[12:13]
	v_add_f32_e32 v122, 1.0, v122
	v_rcp_f32_e32 v122, v122
	v_mad_i64_i32 v[162:163], s[42:43], v142, s65, v[154:155]
	v_add_u32_e32 v143, 0x80, v142
	v_mul_f32_e32 v122, v164, v122
	v_mul_f32_e32 v126, v122, v165
	v_mov_b32_e32 v122, v127
	v_pk_mul_f32 v[122:123], v[158:159], v[122:123] op_sel_hi:[0,1]
	v_mul_f32_e32 v127, 0xbfb8aa3b, v122
	v_exp_f32_e32 v127, v127
	s_mov_b64 s[70:71], -1
	s_andn2_b64 vcc, exec, s[4:5]
	v_add_f32_e32 v127, 1.0, v127
	v_rcp_f32_e32 v127, v127
	s_nop 0
	v_mul_f32_e32 v122, v122, v127
	v_mul_f32_e32 v127, v122, v123
	v_mov_b32_e32 v122, v128
	v_mov_b32_e32 v123, v124
	v_pk_mul_f32 v[122:123], v[158:159], v[122:123] op_sel_hi:[0,1]
	v_mul_f32_e32 v124, 0xbfb8aa3b, v122
	v_exp_f32_e32 v124, v124
	s_nop 0
	v_add_f32_e32 v124, 1.0, v124
	v_rcp_f32_e32 v124, v124
	s_nop 0
	v_mul_f32_e32 v122, v122, v124
	v_mov_b32_e32 v124, v129
	v_mul_f32_e32 v128, v122, v123
	v_pk_mul_f32 v[122:123], v[158:159], v[124:125] op_sel_hi:[0,1]
	v_mul_f32_e32 v124, 0xbfb8aa3b, v122
	v_exp_f32_e32 v124, v124
	s_nop 0
	v_add_f32_e32 v124, 1.0, v124
	v_rcp_f32_e32 v124, v124
	s_nop 0
	v_mul_f32_e32 v122, v122, v124
	v_mul_f32_e32 v124, v122, v123
	v_mov_b32_e32 v122, v118
	v_mov_b32_e32 v123, v114
	v_pk_mul_f32 v[122:123], v[158:159], v[122:123] op_sel_hi:[0,1]
	v_mul_f32_e32 v114, 0xbfb8aa3b, v122
	v_exp_f32_e32 v114, v114
	s_nop 0
	v_add_f32_e32 v114, 1.0, v114
	v_rcp_f32_e32 v114, v114
	s_nop 0
	v_mul_f32_e32 v114, v122, v114
	v_mul_f32_e32 v118, v114, v123
	v_mov_b32_e32 v114, v119
	v_pk_mul_f32 v[114:115], v[158:159], v[114:115] op_sel_hi:[0,1]
	v_mul_f32_e32 v119, 0xbfb8aa3b, v114
	v_exp_f32_e32 v119, v119
	s_nop 0
	v_add_f32_e32 v119, 1.0, v119
	v_rcp_f32_e32 v119, v119
	s_nop 0
	v_mul_f32_e32 v114, v114, v119
	v_mul_f32_e32 v119, v114, v115
	v_mov_b32_e32 v114, v120
	v_mov_b32_e32 v115, v116
	v_pk_mul_f32 v[114:115], v[158:159], v[114:115] op_sel_hi:[0,1]
	v_mul_f32_e32 v116, 0xbfb8aa3b, v114
	v_exp_f32_e32 v116, v116
	s_nop 0
	v_add_f32_e32 v116, 1.0, v116
	v_rcp_f32_e32 v116, v116
	s_nop 0
	v_mul_f32_e32 v114, v114, v116
	v_mov_b32_e32 v116, v121
	v_mul_f32_e32 v122, v114, v115
	v_pk_mul_f32 v[114:115], v[158:159], v[116:117] op_sel_hi:[0,1]
	v_mul_f32_e32 v116, 0xbfb8aa3b, v114
	v_exp_f32_e32 v116, v116
	s_nop 0
	v_add_f32_e32 v116, 1.0, v116
	v_rcp_f32_e32 v116, v116
	s_nop 0
	v_mul_f32_e32 v114, v114, v116
	v_mul_f32_e32 v123, v114, v115
	v_lshlrev_b64 v[114:115], 1, v[160:161]
	v_lshl_add_u64 v[120:121], v[162:163], 0, v[114:115]
	v_cvt_pk_bf16_f32 v116, v126, v127
	v_cvt_pk_bf16_f32 v117, v128, v124
	v_cvt_pk_bf16_f32 v118, v118, v119
	v_cvt_pk_bf16_f32 v119, v122, v123
	v_subrev_u32_e32 v239, s12, v120
	global_store_dwordx4 v239, v[116:119], s[12:13]
	s_nop 1
	v_mov_b32_e32 v118, v110
	v_mov_b32_e32 v119, v106
	v_pk_mul_f32 v[118:119], v[156:157], v[118:119] op_sel_hi:[0,1]
	v_mul_f32_e32 v106, 0xbfb8aa3b, v118
	v_exp_f32_e32 v106, v106
	v_or_b32_e32 v116, 16, v142
	v_mad_i64_i32 v[116:117], s[42:43], v116, s65, v[154:155]
	v_add_f32_e32 v106, 1.0, v106
	v_rcp_f32_e32 v106, v106
	s_nop 0
	v_mul_f32_e32 v106, v118, v106
	v_mul_f32_e32 v110, v106, v119
	v_mov_b32_e32 v106, v111
	v_pk_mul_f32 v[106:107], v[156:157], v[106:107] op_sel_hi:[0,1]
	v_mul_f32_e32 v111, 0xbfb8aa3b, v106
	v_exp_f32_e32 v111, v111
	s_nop 0
	v_add_f32_e32 v111, 1.0, v111
	v_rcp_f32_e32 v111, v111
	s_nop 0
	v_mul_f32_e32 v106, v106, v111
	v_mul_f32_e32 v111, v106, v107
	v_mov_b32_e32 v106, v112
	v_mov_b32_e32 v107, v108
	v_pk_mul_f32 v[106:107], v[156:157], v[106:107] op_sel_hi:[0,1]
	v_mul_f32_e32 v108, 0xbfb8aa3b, v106
	v_exp_f32_e32 v108, v108
	s_nop 0
	v_add_f32_e32 v108, 1.0, v108
	v_rcp_f32_e32 v108, v108
	s_nop 0
	v_mul_f32_e32 v106, v106, v108
	v_mov_b32_e32 v108, v113
	v_mul_f32_e32 v112, v106, v107
	v_pk_mul_f32 v[106:107], v[156:157], v[108:109] op_sel_hi:[0,1]
	v_mul_f32_e32 v108, 0xbfb8aa3b, v106
	v_exp_f32_e32 v108, v108
	s_nop 0
	v_add_f32_e32 v108, 1.0, v108
	v_rcp_f32_e32 v108, v108
	s_nop 0
	v_mul_f32_e32 v106, v106, v108
	v_mul_f32_e32 v108, v106, v107
	v_mov_b32_e32 v106, v102
	v_mov_b32_e32 v107, v98
	v_pk_mul_f32 v[106:107], v[156:157], v[106:107] op_sel_hi:[0,1]
	v_mul_f32_e32 v98, 0xbfb8aa3b, v106
	v_exp_f32_e32 v98, v98
	s_nop 0
	v_add_f32_e32 v98, 1.0, v98
	v_rcp_f32_e32 v98, v98
	s_nop 0
	v_mul_f32_e32 v98, v106, v98
	v_mul_f32_e32 v106, v98, v107
	v_mov_b32_e32 v98, v103
	v_pk_mul_f32 v[98:99], v[156:157], v[98:99] op_sel_hi:[0,1]
	v_mul_f32_e32 v102, 0xbfb8aa3b, v98
	v_exp_f32_e32 v102, v102
	s_nop 0
	v_add_f32_e32 v102, 1.0, v102
	v_rcp_f32_e32 v102, v102
	s_nop 0
	v_mul_f32_e32 v98, v98, v102
	v_mul_f32_e32 v107, v98, v99
	v_mov_b32_e32 v98, v104
	v_mov_b32_e32 v99, v100
	v_pk_mul_f32 v[98:99], v[156:157], v[98:99] op_sel_hi:[0,1]
	v_mul_f32_e32 v100, 0xbfb8aa3b, v98
	v_exp_f32_e32 v100, v100
	v_lshl_add_u64 v[102:103], v[116:117], 0, v[114:115]
	v_add_f32_e32 v100, 1.0, v100
	v_rcp_f32_e32 v100, v100
	s_nop 0
	v_mul_f32_e32 v98, v98, v100
	v_mov_b32_e32 v100, v105
	v_mul_f32_e32 v104, v98, v99
	v_pk_mul_f32 v[98:99], v[156:157], v[100:101] op_sel_hi:[0,1]
	v_mul_f32_e32 v100, 0xbfb8aa3b, v98
	v_exp_f32_e32 v100, v100
	s_nop 0
	v_add_f32_e32 v100, 1.0, v100
	v_rcp_f32_e32 v100, v100
	s_nop 0
	v_mul_f32_e32 v98, v98, v100
	v_mul_f32_e32 v101, v98, v99
	v_cvt_pk_bf16_f32 v98, v110, v111
	v_cvt_pk_bf16_f32 v99, v112, v108
; __device__ __forceinline__ unsigned cvt_pk_bf16(float lo, float hi) { unsigned r; asm volatile("v_cvt_pk_bf16_f32 %0, %1, %2" : "=v"(r) : "v"(lo), "v"(hi)); return r; }
;     __device__ __forceinline__ void operator()(const f32x4 (&acc)[2][2][4][2], const Unit& u, int wr, int wc, int fr, int fq, const float (&rsv)[8]) const {
;     ...
;             for (int m = 0; m < 4; ++m) { bf16_t* rowp = O + (size_t)(row0 + ai * HALF + m * 16) * ldc + col0; float r[8]; const float rr = rsv[ai * 4 + m];
; #pragma unroll
;                 for (int n = 0; n < 2; ++n)
; #pragma unroll
;                     for (int j = 0; j < 4; ++j) { const float g = acc[ai][0][m][n][j] * rr, up = acc[ai][1][m][n][j] * rr;
;                         const float e = __builtin_amdgcn_exp2f(g * -1.4426950408889634f); r[n * 4 + j] = g * __builtin_amdgcn_rcpf(1.0f + e) * up; }
;                 u32x4 w; w.x = cvt_pk_bf16(r[0], r[1]); w.y = cvt_pk_bf16(r[2], r[3]); w.z = cvt_pk_bf16(r[4], r[5]); w.w = cvt_pk_bf16(r[6], r[7]);
;                 *(u32x4*)rowp = w; }
	v_cvt_pk_bf16_f32 v100, v106, v107
	v_cvt_pk_bf16_f32 v101, v104, v101
	v_subrev_u32_e32 v239, s12, v102
	global_store_dwordx4 v239, v[98:101], s[12:13]
	s_nop 1
	v_mov_b32_e32 v100, v94
	v_mov_b32_e32 v101, v90
	v_pk_mul_f32 v[100:101], v[152:153], v[100:101] op_sel_hi:[0,1]
	v_mul_f32_e32 v90, 0xbfb8aa3b, v100
	v_exp_f32_e32 v90, v90
	v_or_b32_e32 v98, 32, v142
	v_mad_i64_i32 v[98:99], s[42:43], v98, s65, v[154:155]
	v_add_f32_e32 v90, 1.0, v90
	v_rcp_f32_e32 v90, v90
	s_nop 0
	v_mul_f32_e32 v90, v100, v90
	v_mul_f32_e32 v94, v90, v101
	v_mov_b32_e32 v90, v95
	v_pk_mul_f32 v[90:91], v[152:153], v[90:91] op_sel_hi:[0,1]
	v_mul_f32_e32 v95, 0xbfb8aa3b, v90
	v_exp_f32_e32 v95, v95
	s_nop 0
	v_add_f32_e32 v95, 1.0, v95
	v_rcp_f32_e32 v95, v95
	s_nop 0
	v_mul_f32_e32 v90, v90, v95
	v_mul_f32_e32 v95, v90, v91
	v_mov_b32_e32 v90, v96
	v_mov_b32_e32 v91, v92
	v_pk_mul_f32 v[90:91], v[152:153], v[90:91] op_sel_hi:[0,1]
	v_mul_f32_e32 v92, 0xbfb8aa3b, v90
	v_exp_f32_e32 v92, v92
	s_nop 0
	v_add_f32_e32 v92, 1.0, v92
	v_rcp_f32_e32 v92, v92
	s_nop 0
	v_mul_f32_e32 v90, v90, v92
	v_mov_b32_e32 v92, v97
	v_mul_f32_e32 v96, v90, v91
	v_pk_mul_f32 v[90:91], v[152:153], v[92:93] op_sel_hi:[0,1]
	v_mul_f32_e32 v92, 0xbfb8aa3b, v90
	v_exp_f32_e32 v92, v92
	s_nop 0
	v_add_f32_e32 v92, 1.0, v92
	v_rcp_f32_e32 v92, v92
	s_nop 0
	v_mul_f32_e32 v90, v90, v92
	v_mul_f32_e32 v92, v90, v91
	v_mov_b32_e32 v90, v86
	v_mov_b32_e32 v91, v82
	v_pk_mul_f32 v[90:91], v[152:153], v[90:91] op_sel_hi:[0,1]
	v_mul_f32_e32 v82, 0xbfb8aa3b, v90
	v_exp_f32_e32 v82, v82
	s_nop 0
	v_add_f32_e32 v82, 1.0, v82
	v_rcp_f32_e32 v82, v82
	s_nop 0
	v_mul_f32_e32 v82, v90, v82
	v_mul_f32_e32 v90, v82, v91
	v_mov_b32_e32 v82, v87
	v_pk_mul_f32 v[82:83], v[152:153], v[82:83] op_sel_hi:[0,1]
	v_mul_f32_e32 v86, 0xbfb8aa3b, v82
	v_exp_f32_e32 v86, v86
	s_nop 0
	v_add_f32_e32 v86, 1.0, v86
	v_rcp_f32_e32 v86, v86
	s_nop 0
	v_mul_f32_e32 v82, v82, v86
	v_mul_f32_e32 v91, v82, v83
	v_mov_b32_e32 v82, v88
	v_mov_b32_e32 v83, v84
	v_pk_mul_f32 v[82:83], v[152:153], v[82:83] op_sel_hi:[0,1]
	v_mul_f32_e32 v84, 0xbfb8aa3b, v82
	v_exp_f32_e32 v84, v84
	v_lshl_add_u64 v[86:87], v[98:99], 0, v[114:115]
	v_add_f32_e32 v84, 1.0, v84
	v_rcp_f32_e32 v84, v84
	s_nop 0
	v_mul_f32_e32 v82, v82, v84
	v_mov_b32_e32 v84, v89
	v_mul_f32_e32 v88, v82, v83
	v_pk_mul_f32 v[82:83], v[152:153], v[84:85] op_sel_hi:[0,1]
	v_mul_f32_e32 v84, 0xbfb8aa3b, v82
	v_exp_f32_e32 v84, v84
	s_nop 0
	v_add_f32_e32 v84, 1.0, v84
	v_rcp_f32_e32 v84, v84
	s_nop 0
	v_mul_f32_e32 v82, v82, v84
	v_mul_f32_e32 v85, v82, v83
	v_cvt_pk_bf16_f32 v82, v94, v95
	v_cvt_pk_bf16_f32 v83, v96, v92
	v_cvt_pk_bf16_f32 v84, v90, v91
	v_cvt_pk_bf16_f32 v85, v88, v85
	v_subrev_u32_e32 v239, s12, v86
	global_store_dwordx4 v239, v[82:85], s[12:13]
	s_nop 1
	v_mov_b32_e32 v84, v78
	v_mov_b32_e32 v85, v74
	v_pk_mul_f32 v[84:85], v[150:151], v[84:85] op_sel_hi:[0,1]
	v_mul_f32_e32 v74, 0xbfb8aa3b, v84
	v_exp_f32_e32 v74, v74
	v_or_b32_e32 v82, 48, v142
	v_mad_i64_i32 v[82:83], s[42:43], v82, s65, v[154:155]
	v_add_f32_e32 v74, 1.0, v74
	v_rcp_f32_e32 v74, v74
	s_nop 0
	v_mul_f32_e32 v74, v84, v74
	v_mul_f32_e32 v78, v74, v85
	v_mov_b32_e32 v74, v79
	v_pk_mul_f32 v[74:75], v[150:151], v[74:75] op_sel_hi:[0,1]
	v_mul_f32_e32 v79, 0xbfb8aa3b, v74
	v_exp_f32_e32 v79, v79
	s_nop 0
	v_add_f32_e32 v79, 1.0, v79
	v_rcp_f32_e32 v79, v79
	s_nop 0
	v_mul_f32_e32 v74, v74, v79
	v_mul_f32_e32 v79, v74, v75
	v_mov_b32_e32 v74, v80
	v_mov_b32_e32 v75, v76
	v_pk_mul_f32 v[74:75], v[150:151], v[74:75] op_sel_hi:[0,1]
	v_mul_f32_e32 v76, 0xbfb8aa3b, v74
	v_exp_f32_e32 v76, v76
	s_nop 0
	v_add_f32_e32 v76, 1.0, v76
	v_rcp_f32_e32 v76, v76
	s_nop 0
	v_mul_f32_e32 v74, v74, v76
	v_mov_b32_e32 v76, v81
	v_mul_f32_e32 v80, v74, v75
	v_pk_mul_f32 v[74:75], v[150:151], v[76:77] op_sel_hi:[0,1]
	v_mul_f32_e32 v76, 0xbfb8aa3b, v74
	v_exp_f32_e32 v76, v76
	s_nop 0
	v_add_f32_e32 v76, 1.0, v76
	v_rcp_f32_e32 v76, v76
	s_nop 0
	v_mul_f32_e32 v74, v74, v76
	v_mul_f32_e32 v76, v74, v75
	v_mov_b32_e32 v74, v70
	v_mov_b32_e32 v75, v66
	v_pk_mul_f32 v[74:75], v[150:151], v[74:75] op_sel_hi:[0,1]
	v_mul_f32_e32 v66, 0xbfb8aa3b, v74
	v_exp_f32_e32 v66, v66
	s_nop 0
	v_add_f32_e32 v66, 1.0, v66
	v_rcp_f32_e32 v66, v66
	s_nop 0
	v_mul_f32_e32 v66, v74, v66
	v_mul_f32_e32 v74, v66, v75
	v_mov_b32_e32 v66, v71
	v_pk_mul_f32 v[66:67], v[150:151], v[66:67] op_sel_hi:[0,1]
	v_mul_f32_e32 v70, 0xbfb8aa3b, v66
	v_exp_f32_e32 v70, v70
	s_nop 0
	v_add_f32_e32 v70, 1.0, v70
	v_rcp_f32_e32 v70, v70
	s_nop 0
	v_mul_f32_e32 v66, v66, v70
	v_mul_f32_e32 v75, v66, v67
	v_mov_b32_e32 v66, v72
	v_mov_b32_e32 v67, v68
	v_pk_mul_f32 v[66:67], v[150:151], v[66:67] op_sel_hi:[0,1]
	v_mul_f32_e32 v68, 0xbfb8aa3b, v66
	v_exp_f32_e32 v68, v68
	v_lshl_add_u64 v[70:71], v[82:83], 0, v[114:115]
	v_add_f32_e32 v68, 1.0, v68
	v_rcp_f32_e32 v68, v68
	s_nop 0
	v_mul_f32_e32 v66, v66, v68
	v_mov_b32_e32 v68, v73
	v_mul_f32_e32 v72, v66, v67
	v_pk_mul_f32 v[66:67], v[150:151], v[68:69] op_sel_hi:[0,1]
	v_mul_f32_e32 v68, 0xbfb8aa3b, v66
	v_exp_f32_e32 v68, v68
	s_nop 0
	v_add_f32_e32 v68, 1.0, v68
	v_rcp_f32_e32 v68, v68
	s_nop 0
	v_mul_f32_e32 v66, v66, v68
	v_mul_f32_e32 v69, v66, v67
	v_cvt_pk_bf16_f32 v66, v78, v79
	v_cvt_pk_bf16_f32 v67, v80, v76
	v_cvt_pk_bf16_f32 v68, v74, v75
	v_cvt_pk_bf16_f32 v69, v72, v69
	v_subrev_u32_e32 v239, s12, v70
	global_store_dwordx4 v239, v[66:69], s[12:13]
	s_nop 1
	v_mov_b32_e32 v68, v62
	v_mov_b32_e32 v69, v58
	v_pk_mul_f32 v[68:69], v[148:149], v[68:69] op_sel_hi:[0,1]
	v_mul_f32_e32 v58, 0xbfb8aa3b, v68
	v_exp_f32_e32 v58, v58
	v_mad_i64_i32 v[66:67], s[42:43], v143, s65, v[154:155]
; __device__ __forceinline__ unsigned cvt_pk_bf16(float lo, float hi) { unsigned r; asm volatile("v_cvt_pk_bf16_f32 %0, %1, %2" : "=v"(r) : "v"(lo), "v"(hi)); return r; }
;     __device__ __forceinline__ void operator()(const f32x4 (&acc)[2][2][4][2], const Unit& u, int wr, int wc, int fr, int fq, const float (&rsv)[8]) const {
;     ...
;             for (int m = 0; m < 4; ++m) { bf16_t* rowp = O + (size_t)(row0 + ai * HALF + m * 16) * ldc + col0; float r[8]; const float rr = rsv[ai * 4 + m];
; #pragma unroll
;                 for (int n = 0; n < 2; ++n)
; #pragma unroll
;                     for (int j = 0; j < 4; ++j) { const float g = acc[ai][0][m][n][j] * rr, up = acc[ai][1][m][n][j] * rr;
;                         const float e = __builtin_amdgcn_exp2f(g * -1.4426950408889634f); r[n * 4 + j] = g * __builtin_amdgcn_rcpf(1.0f + e) * up; }
;                 u32x4 w; w.x = cvt_pk_bf16(r[0], r[1]); w.y = cvt_pk_bf16(r[2], r[3]); w.z = cvt_pk_bf16(r[4], r[5]); w.w = cvt_pk_bf16(r[6], r[7]);
;                 *(u32x4*)rowp = w; }
	v_add_f32_e32 v58, 1.0, v58
	v_rcp_f32_e32 v58, v58
	s_nop 0
	v_mul_f32_e32 v58, v68, v58
	v_mul_f32_e32 v62, v58, v69
	v_mov_b32_e32 v58, v63
	v_pk_mul_f32 v[58:59], v[148:149], v[58:59] op_sel_hi:[0,1]
	v_mul_f32_e32 v63, 0xbfb8aa3b, v58
	v_exp_f32_e32 v63, v63
	s_nop 0
	v_add_f32_e32 v63, 1.0, v63
	v_rcp_f32_e32 v63, v63
	s_nop 0
	v_mul_f32_e32 v58, v58, v63
	v_mul_f32_e32 v63, v58, v59
	v_mov_b32_e32 v58, v64
	v_mov_b32_e32 v59, v60
	v_pk_mul_f32 v[58:59], v[148:149], v[58:59] op_sel_hi:[0,1]
	v_mul_f32_e32 v60, 0xbfb8aa3b, v58
	v_exp_f32_e32 v60, v60
	s_nop 0
	v_add_f32_e32 v60, 1.0, v60
	v_rcp_f32_e32 v60, v60
	s_nop 0
	v_mul_f32_e32 v58, v58, v60
	v_mov_b32_e32 v60, v65
	v_mul_f32_e32 v64, v58, v59
	v_pk_mul_f32 v[58:59], v[148:149], v[60:61] op_sel_hi:[0,1]
	v_mul_f32_e32 v60, 0xbfb8aa3b, v58
	v_exp_f32_e32 v60, v60
	s_nop 0
	v_add_f32_e32 v60, 1.0, v60
	v_rcp_f32_e32 v60, v60
	s_nop 0
	v_mul_f32_e32 v58, v58, v60
	v_mul_f32_e32 v60, v58, v59
	v_mov_b32_e32 v58, v54
	v_mov_b32_e32 v59, v50
	v_pk_mul_f32 v[58:59], v[148:149], v[58:59] op_sel_hi:[0,1]
	v_mul_f32_e32 v50, 0xbfb8aa3b, v58
	v_exp_f32_e32 v50, v50
	s_nop 0
	v_add_f32_e32 v50, 1.0, v50
	v_rcp_f32_e32 v50, v50
	s_nop 0
	v_mul_f32_e32 v50, v58, v50
	v_mul_f32_e32 v58, v50, v59
	v_mov_b32_e32 v50, v55
	v_pk_mul_f32 v[50:51], v[148:149], v[50:51] op_sel_hi:[0,1]
	v_mul_f32_e32 v54, 0xbfb8aa3b, v50
	v_exp_f32_e32 v54, v54
	s_nop 0
	v_add_f32_e32 v54, 1.0, v54
	v_rcp_f32_e32 v54, v54
	s_nop 0
	v_mul_f32_e32 v50, v50, v54
	v_mul_f32_e32 v59, v50, v51
	v_mov_b32_e32 v50, v56
	v_mov_b32_e32 v51, v52
	v_pk_mul_f32 v[50:51], v[148:149], v[50:51] op_sel_hi:[0,1]
	v_mul_f32_e32 v52, 0xbfb8aa3b, v50
	v_exp_f32_e32 v52, v52
	v_lshl_add_u64 v[54:55], v[66:67], 0, v[114:115]
	v_add_f32_e32 v52, 1.0, v52
	v_rcp_f32_e32 v52, v52
	s_nop 0
	v_mul_f32_e32 v50, v50, v52
	v_mov_b32_e32 v52, v57
	v_mul_f32_e32 v56, v50, v51
	v_pk_mul_f32 v[50:51], v[148:149], v[52:53] op_sel_hi:[0,1]
	v_mul_f32_e32 v52, 0xbfb8aa3b, v50
	v_exp_f32_e32 v52, v52
	s_nop 0
	v_add_f32_e32 v52, 1.0, v52
	v_rcp_f32_e32 v52, v52
	s_nop 0
	v_mul_f32_e32 v50, v50, v52
	v_mul_f32_e32 v53, v50, v51
	v_cvt_pk_bf16_f32 v50, v62, v63
	v_cvt_pk_bf16_f32 v51, v64, v60
	v_cvt_pk_bf16_f32 v52, v58, v59
	v_cvt_pk_bf16_f32 v53, v56, v53
	v_subrev_u32_e32 v239, s12, v54
	global_store_dwordx4 v239, v[50:53], s[12:13]
	s_nop 1
	v_mov_b32_e32 v52, v46
	v_mov_b32_e32 v53, v42
	v_pk_mul_f32 v[52:53], v[146:147], v[52:53] op_sel_hi:[0,1]
	v_mul_f32_e32 v42, 0xbfb8aa3b, v52
	v_exp_f32_e32 v42, v42
	v_add_u32_e32 v50, 0x90, v142
	v_mad_i64_i32 v[50:51], s[42:43], v50, s65, v[154:155]
	v_add_f32_e32 v42, 1.0, v42
	v_rcp_f32_e32 v42, v42
	s_nop 0
	v_mul_f32_e32 v42, v52, v42
	v_mul_f32_e32 v46, v42, v53
	v_mov_b32_e32 v42, v47
	v_pk_mul_f32 v[42:43], v[146:147], v[42:43] op_sel_hi:[0,1]
	v_mul_f32_e32 v47, 0xbfb8aa3b, v42
	v_exp_f32_e32 v47, v47
	s_nop 0
	v_add_f32_e32 v47, 1.0, v47
	v_rcp_f32_e32 v47, v47
	s_nop 0
	v_mul_f32_e32 v42, v42, v47
	v_mul_f32_e32 v47, v42, v43
	v_mov_b32_e32 v42, v48
	v_mov_b32_e32 v43, v44
	v_pk_mul_f32 v[42:43], v[146:147], v[42:43] op_sel_hi:[0,1]
	v_mul_f32_e32 v44, 0xbfb8aa3b, v42
	v_exp_f32_e32 v44, v44
	s_nop 0
	v_add_f32_e32 v44, 1.0, v44
	v_rcp_f32_e32 v44, v44
	s_nop 0
	v_mul_f32_e32 v42, v42, v44
	v_mov_b32_e32 v44, v49
	v_mul_f32_e32 v48, v42, v43
	v_pk_mul_f32 v[42:43], v[146:147], v[44:45] op_sel_hi:[0,1]
	v_mul_f32_e32 v44, 0xbfb8aa3b, v42
	v_exp_f32_e32 v44, v44
	s_nop 0
	v_add_f32_e32 v44, 1.0, v44
	v_rcp_f32_e32 v44, v44
	s_nop 0
	v_mul_f32_e32 v42, v42, v44
	v_mul_f32_e32 v44, v42, v43
	v_mov_b32_e32 v42, v38
	v_mov_b32_e32 v43, v34
	v_pk_mul_f32 v[42:43], v[146:147], v[42:43] op_sel_hi:[0,1]
	v_mul_f32_e32 v34, 0xbfb8aa3b, v42
	v_exp_f32_e32 v34, v34
	s_nop 0
	v_add_f32_e32 v34, 1.0, v34
	v_rcp_f32_e32 v34, v34
	s_nop 0
	v_mul_f32_e32 v34, v42, v34
	v_mul_f32_e32 v42, v34, v43
	v_mov_b32_e32 v34, v39
	v_pk_mul_f32 v[34:35], v[146:147], v[34:35] op_sel_hi:[0,1]
	v_mul_f32_e32 v38, 0xbfb8aa3b, v34
	v_exp_f32_e32 v38, v38
	s_nop 0
	v_add_f32_e32 v38, 1.0, v38
	v_rcp_f32_e32 v38, v38
	s_nop 0
	v_mul_f32_e32 v34, v34, v38
	v_mul_f32_e32 v43, v34, v35
	v_mov_b32_e32 v34, v40
	v_mov_b32_e32 v35, v36
	v_pk_mul_f32 v[34:35], v[146:147], v[34:35] op_sel_hi:[0,1]
	v_mul_f32_e32 v36, 0xbfb8aa3b, v34
	v_exp_f32_e32 v36, v36
	v_lshl_add_u64 v[38:39], v[50:51], 0, v[114:115]
	v_add_f32_e32 v36, 1.0, v36
	v_rcp_f32_e32 v36, v36
	s_nop 0
	v_mul_f32_e32 v34, v34, v36
	v_mov_b32_e32 v36, v41
	v_mul_f32_e32 v40, v34, v35
	v_pk_mul_f32 v[34:35], v[146:147], v[36:37] op_sel_hi:[0,1]
	v_mul_f32_e32 v36, 0xbfb8aa3b, v34
	v_exp_f32_e32 v36, v36
	s_nop 0
	v_add_f32_e32 v36, 1.0, v36
	v_rcp_f32_e32 v36, v36
	s_nop 0
	v_mul_f32_e32 v34, v34, v36
	v_mul_f32_e32 v37, v34, v35
	v_cvt_pk_bf16_f32 v34, v46, v47
	v_cvt_pk_bf16_f32 v35, v48, v44
	v_cvt_pk_bf16_f32 v36, v42, v43
	v_cvt_pk_bf16_f32 v37, v40, v37
	v_subrev_u32_e32 v239, s12, v38
	global_store_dwordx4 v239, v[34:37], s[12:13]
	s_nop 1
	v_mov_b32_e32 v36, v30
	v_mov_b32_e32 v37, v26
	v_pk_mul_f32 v[36:37], v[144:145], v[36:37] op_sel_hi:[0,1]
	v_mul_f32_e32 v26, 0xbfb8aa3b, v36
; __device__ __forceinline__ unsigned cvt_pk_bf16(float lo, float hi) { unsigned r; asm volatile("v_cvt_pk_bf16_f32 %0, %1, %2" : "=v"(r) : "v"(lo), "v"(hi)); return r; }
; #define PG8_BAR __builtin_amdgcn_s_barrier()
;     __device__ __forceinline__ void operator()(const f32x4 (&acc)[2][2][4][2], const Unit& u, int wr, int wc, int fr, int fq, const float (&rsv)[8]) const {
;     ...
;             for (int m = 0; m < 4; ++m) { bf16_t* rowp = O + (size_t)(row0 + ai * HALF + m * 16) * ldc + col0; float r[8]; const float rr = rsv[ai * 4 + m];
; #pragma unroll
;                 for (int n = 0; n < 2; ++n)
; #pragma unroll
;                     for (int j = 0; j < 4; ++j) { const float g = acc[ai][0][m][n][j] * rr, up = acc[ai][1][m][n][j] * rr;
;                         const float e = __builtin_amdgcn_exp2f(g * -1.4426950408889634f); r[n * 4 + j] = g * __builtin_amdgcn_rcpf(1.0f + e) * up; }
;                 u32x4 w; w.x = cvt_pk_bf16(r[0], r[1]); w.y = cvt_pk_bf16(r[2], r[3]); w.z = cvt_pk_bf16(r[4], r[5]); w.w = cvt_pk_bf16(r[6], r[7]);
;                 *(u32x4*)rowp = w; }
; template <class Epi, class Sched, bool ALIGN_EPI = false, bool SP2 = false>
; __device__ __forceinline__ void gemm_phase(PG8_LAS unsigned char* lds, const Gemm g, const Sched& S, const Epi& E, const int tid_in) {
;     ...
;         if (!has_next) break;
; #pragma unroll
;         for (int a = 0; a < 2; ++a)
; #pragma unroll
;             for (int b = 0; b < 2; ++b)
; #pragma unroll
;                 for (int m = 0; m < 4; ++m)
; #pragma unroll
;                     for (int n = 0; n < 2; ++n) acc[a][b][m][n] = (f32x4){0.f, 0.f, 0.f, 0.f};
;         cur = nxt; cA = nA; cB = nB; ++ui;
;         if constexpr (ALIGN_EPI) { if (wr == 1) PG8_BAR; }
	v_exp_f32_e32 v26, v26
	v_add_u32_e32 v34, 0xa0, v142
	v_mad_i64_i32 v[34:35], s[42:43], v34, s65, v[154:155]
	v_add_f32_e32 v26, 1.0, v26
	v_rcp_f32_e32 v26, v26
	s_nop 0
	v_mul_f32_e32 v26, v36, v26
	v_mul_f32_e32 v30, v26, v37
	v_mov_b32_e32 v26, v31
	v_pk_mul_f32 v[26:27], v[144:145], v[26:27] op_sel_hi:[0,1]
	v_mul_f32_e32 v31, 0xbfb8aa3b, v26
	v_exp_f32_e32 v31, v31
	s_nop 0
	v_add_f32_e32 v31, 1.0, v31
	v_rcp_f32_e32 v31, v31
	s_nop 0
	v_mul_f32_e32 v26, v26, v31
	v_mul_f32_e32 v31, v26, v27
	v_mov_b32_e32 v26, v32
	v_mov_b32_e32 v27, v28
	v_pk_mul_f32 v[26:27], v[144:145], v[26:27] op_sel_hi:[0,1]
	v_mul_f32_e32 v28, 0xbfb8aa3b, v26
	v_exp_f32_e32 v28, v28
	s_nop 0
	v_add_f32_e32 v28, 1.0, v28
	v_rcp_f32_e32 v28, v28
	s_nop 0
	v_mul_f32_e32 v26, v26, v28
	v_mov_b32_e32 v28, v33
	v_mul_f32_e32 v32, v26, v27
	v_pk_mul_f32 v[26:27], v[144:145], v[28:29] op_sel_hi:[0,1]
	v_mul_f32_e32 v28, 0xbfb8aa3b, v26
	v_exp_f32_e32 v28, v28
	s_nop 0
	v_add_f32_e32 v28, 1.0, v28
	v_rcp_f32_e32 v28, v28
	s_nop 0
	v_mul_f32_e32 v26, v26, v28
	v_mul_f32_e32 v28, v26, v27
	v_mov_b32_e32 v26, v22
	v_mov_b32_e32 v27, v18
	v_pk_mul_f32 v[26:27], v[144:145], v[26:27] op_sel_hi:[0,1]
	v_mul_f32_e32 v18, 0xbfb8aa3b, v26
	v_exp_f32_e32 v18, v18
	s_nop 0
	v_add_f32_e32 v18, 1.0, v18
	v_rcp_f32_e32 v18, v18
	s_nop 0
	v_mul_f32_e32 v18, v26, v18
	v_mul_f32_e32 v26, v18, v27
	v_mov_b32_e32 v18, v23
	v_pk_mul_f32 v[18:19], v[144:145], v[18:19] op_sel_hi:[0,1]
	v_mul_f32_e32 v22, 0xbfb8aa3b, v18
	v_exp_f32_e32 v22, v22
	s_nop 0
	v_add_f32_e32 v22, 1.0, v22
	v_rcp_f32_e32 v22, v22
	s_nop 0
	v_mul_f32_e32 v18, v18, v22
	v_mul_f32_e32 v27, v18, v19
	v_mov_b32_e32 v18, v24
	v_mov_b32_e32 v19, v20
	v_pk_mul_f32 v[18:19], v[144:145], v[18:19] op_sel_hi:[0,1]
	v_mul_f32_e32 v20, 0xbfb8aa3b, v18
	v_exp_f32_e32 v20, v20
	v_lshl_add_u64 v[22:23], v[34:35], 0, v[114:115]
	v_add_f32_e32 v20, 1.0, v20
	v_rcp_f32_e32 v20, v20
	s_nop 0
	v_mul_f32_e32 v18, v18, v20
	v_mov_b32_e32 v20, v25
	v_mul_f32_e32 v24, v18, v19
	v_pk_mul_f32 v[18:19], v[144:145], v[20:21] op_sel_hi:[0,1]
	v_mul_f32_e32 v20, 0xbfb8aa3b, v18
	v_exp_f32_e32 v20, v20
	s_nop 0
	v_add_f32_e32 v20, 1.0, v20
	v_rcp_f32_e32 v20, v20
	s_nop 0
	v_mul_f32_e32 v18, v18, v20
	v_mul_f32_e32 v21, v18, v19
	v_cvt_pk_bf16_f32 v18, v30, v31
	v_cvt_pk_bf16_f32 v19, v32, v28
	v_cvt_pk_bf16_f32 v20, v26, v27
	v_cvt_pk_bf16_f32 v21, v24, v21
	v_subrev_u32_e32 v239, s12, v22
	global_store_dwordx4 v239, v[18:21], s[12:13]
	s_nop 1
	v_mov_b32_e32 v20, v14
	v_mov_b32_e32 v21, v10
	v_pk_mul_f32 v[20:21], v[140:141], v[20:21] op_sel_hi:[0,1]
	v_mul_f32_e32 v10, 0xbfb8aa3b, v20
	v_exp_f32_e32 v10, v10
	v_add_u32_e32 v18, 0xb0, v142
	v_mad_i64_i32 v[18:19], s[42:43], v18, s65, v[154:155]
	v_add_f32_e32 v10, 1.0, v10
	v_rcp_f32_e32 v10, v10
	s_nop 0
	v_mul_f32_e32 v10, v20, v10
	v_mul_f32_e32 v14, v10, v21
	v_mov_b32_e32 v10, v15
	v_pk_mul_f32 v[10:11], v[140:141], v[10:11] op_sel_hi:[0,1]
	v_mul_f32_e32 v15, 0xbfb8aa3b, v10
	v_exp_f32_e32 v15, v15
	s_nop 0
	v_add_f32_e32 v15, 1.0, v15
	v_rcp_f32_e32 v15, v15
	s_nop 0
	v_mul_f32_e32 v10, v10, v15
	v_mul_f32_e32 v15, v10, v11
	v_mov_b32_e32 v10, v16
	v_mov_b32_e32 v11, v12
	v_pk_mul_f32 v[10:11], v[140:141], v[10:11] op_sel_hi:[0,1]
	v_mul_f32_e32 v12, 0xbfb8aa3b, v10
	v_exp_f32_e32 v12, v12
	s_nop 0
	v_add_f32_e32 v12, 1.0, v12
	v_rcp_f32_e32 v12, v12
	s_nop 0
	v_mul_f32_e32 v10, v10, v12
	v_mov_b32_e32 v12, v17
	v_mul_f32_e32 v16, v10, v11
	v_pk_mul_f32 v[10:11], v[140:141], v[12:13] op_sel_hi:[0,1]
	v_mul_f32_e32 v12, 0xbfb8aa3b, v10
	v_exp_f32_e32 v12, v12
	s_nop 0
	v_add_f32_e32 v12, 1.0, v12
	v_rcp_f32_e32 v12, v12
	s_nop 0
	v_mul_f32_e32 v10, v10, v12
	v_mul_f32_e32 v12, v10, v11
	v_mov_b32_e32 v10, v6
	v_mov_b32_e32 v11, v2
	v_pk_mul_f32 v[10:11], v[140:141], v[10:11] op_sel_hi:[0,1]
	v_mul_f32_e32 v2, 0xbfb8aa3b, v10
	v_exp_f32_e32 v2, v2
	s_nop 0
	v_add_f32_e32 v2, 1.0, v2
	v_rcp_f32_e32 v2, v2
	s_nop 0
	v_mul_f32_e32 v2, v10, v2
	v_mul_f32_e32 v10, v2, v11
	v_mov_b32_e32 v2, v7
	v_pk_mul_f32 v[2:3], v[140:141], v[2:3] op_sel_hi:[0,1]
	v_mul_f32_e32 v6, 0xbfb8aa3b, v2
	v_exp_f32_e32 v6, v6
	s_nop 0
	v_add_f32_e32 v6, 1.0, v6
	v_rcp_f32_e32 v6, v6
	s_nop 0
	v_mul_f32_e32 v2, v2, v6
	v_mul_f32_e32 v11, v2, v3
	v_mov_b32_e32 v2, v8
	v_mov_b32_e32 v3, v4
	v_pk_mul_f32 v[2:3], v[140:141], v[2:3] op_sel_hi:[0,1]
	v_mul_f32_e32 v4, 0xbfb8aa3b, v2
	v_exp_f32_e32 v4, v4
	v_lshl_add_u64 v[6:7], v[18:19], 0, v[114:115]
	v_add_f32_e32 v4, 1.0, v4
	v_rcp_f32_e32 v4, v4
	s_nop 0
	v_mul_f32_e32 v2, v2, v4
	v_mov_b32_e32 v4, v9
	v_mul_f32_e32 v8, v2, v3
	v_pk_mul_f32 v[2:3], v[140:141], v[4:5] op_sel_hi:[0,1]
	v_mul_f32_e32 v4, 0xbfb8aa3b, v2
	v_exp_f32_e32 v4, v4
	s_nop 0
	v_add_f32_e32 v4, 1.0, v4
	v_rcp_f32_e32 v4, v4
	s_nop 0
	v_mul_f32_e32 v2, v2, v4
	v_mul_f32_e32 v5, v2, v3
	v_cvt_pk_bf16_f32 v2, v14, v15
	v_cvt_pk_bf16_f32 v3, v16, v12
	v_cvt_pk_bf16_f32 v4, v10, v11
	v_cvt_pk_bf16_f32 v5, v8, v5
	v_subrev_u32_e32 v239, s12, v6
	global_store_dwordx4 v239, v[2:5], s[12:13]
	s_cbranch_vccnz .LBB0_618
	s_andn2_b64 vcc, exec, s[10:11]
	s_cbranch_vccnz .LBB0_617
	s_barrier
	s_branch .LBB0_617

; __device__ __forceinline__ unsigned cvt_pk_bf16(float lo, float hi) { unsigned r; asm volatile("v_cvt_pk_bf16_f32 %0, %1, %2" : "=v"(r) : "v"(lo), "v"(hi)); return r; }
; #define PG8_BAR __builtin_amdgcn_s_barrier()
;     __device__ __forceinline__ void operator()(const f32x4 (&acc)[2][2][4][2], const Unit& u, int wr, int wc, int fr, int fq, const float (&rsv)[8]) const {
;         const int row0 = u.pm * BM + wr * 64 + fr, col0 = u.pn * BM + wc * 32 + 8 * fq;
; #pragma unroll
;         for (int ai = 0; ai < 2; ++ai)
; #pragma unroll
;             for (int m = 0; m < 4; ++m) { bf16_t* rowp = O + (size_t)(row0 + ai * HALF + m * 16) * ldc + col0;
; #pragma unroll
;                 for (int bj = 0; bj < 2; ++bj) { const f32x4 v0 = acc[ai][bj][m][0], v1 = acc[ai][bj][m][1];
;                     u32x4 w; w.x = cvt_pk_bf16(v0[0], v0[1]); w.y = cvt_pk_bf16(v0[2], v0[3]); w.z = cvt_pk_bf16(v1[0], v1[1]); w.w = cvt_pk_bf16(v1[2], v1[3]);
;                     *(u32x4*)(rowp + bj * HALF) = w; } }
;     }
; template <class Epi, class Sched, bool ALIGN_EPI = false, bool SP2 = false>
; __device__ __forceinline__ void gemm_phase(PG8_LAS unsigned char* lds, const Gemm g, const Sched& S, const Epi& E, const int tid_in) {
;     ...
;         if (!has_next) break;
; #pragma unroll
;         for (int a = 0; a < 2; ++a)
; #pragma unroll
;             for (int b = 0; b < 2; ++b)
; #pragma unroll
;                 for (int m = 0; m < 4; ++m)
; #pragma unroll
;                     for (int n = 0; n < 2; ++n) acc[a][b][m][n] = (f32x4){0.f, 0.f, 0.f, 0.f};
;         cur = nxt; cA = nA; cB = nB; ++ui;
;         if constexpr (ALIGN_EPI) { if (wr == 1) PG8_BAR; }
.LBB0_706:
	v_lshl_add_u32 v146, s60, 8, v142
	v_lshl_or_b32 v140, s61, 8, v144
	v_ashrrev_i32_e32 v147, 31, v146
	v_ashrrev_i32_e32 v141, 31, v140
	v_lshlrev_b64 v[148:149], 11, v[146:147]
	v_lshl_add_u64 v[148:149], s[12:13], 0, v[148:149]
	v_lshlrev_b64 v[150:151], 1, v[140:141]
	v_lshl_add_u64 v[140:141], v[148:149], 0, v[150:151]
	v_cvt_pk_bf16_f32 v126, v126, v127
	v_cvt_pk_bf16_f32 v127, v128, v129
	v_cvt_pk_bf16_f32 v128, v122, v123
	v_cvt_pk_bf16_f32 v129, v124, v125
	v_subrev_u32_e32 v218, s12, v140
	global_store_dwordx4 v218, v[126:129], s[12:13]
	v_cvt_pk_bf16_f32 v114, v114, v115
	v_cvt_pk_bf16_f32 v115, v116, v117
	v_cvt_pk_bf16_f32 v116, v106, v107
	v_or_b32_e32 v106, 16, v146
	v_ashrrev_i32_e32 v107, 31, v106
	v_lshlrev_b64 v[106:107], 11, v[106:107]
	v_lshl_add_u64 v[106:107], s[12:13], 0, v[106:107]
	v_cvt_pk_bf16_f32 v117, v108, v109
	v_subrev_u32_e32 v218, s12, v140
	global_store_dwordx4 v218, v[114:117], s[12:13] offset:256
	s_nop 1
	v_lshl_add_u64 v[114:115], v[106:107], 0, v[150:151]
	v_cvt_pk_bf16_f32 v106, v118, v119
	v_cvt_pk_bf16_f32 v107, v120, v121
	v_cvt_pk_bf16_f32 v108, v110, v111
	v_cvt_pk_bf16_f32 v109, v112, v113
	v_subrev_u32_e32 v218, s12, v114
	global_store_dwordx4 v218, v[106:109], s[12:13]
	v_cvt_pk_bf16_f32 v98, v98, v99
	v_cvt_pk_bf16_f32 v99, v100, v101
	v_cvt_pk_bf16_f32 v100, v90, v91
	v_or_b32_e32 v90, 32, v146
	v_ashrrev_i32_e32 v91, 31, v90
	v_lshlrev_b64 v[90:91], 11, v[90:91]
	v_lshl_add_u64 v[90:91], s[12:13], 0, v[90:91]
	v_cvt_pk_bf16_f32 v101, v92, v93
	v_subrev_u32_e32 v218, s12, v114
	global_store_dwordx4 v218, v[98:101], s[12:13] offset:256
	s_nop 1
	v_lshl_add_u64 v[98:99], v[90:91], 0, v[150:151]
	v_cvt_pk_bf16_f32 v90, v102, v103
	v_cvt_pk_bf16_f32 v91, v104, v105
	v_cvt_pk_bf16_f32 v92, v94, v95
	v_cvt_pk_bf16_f32 v93, v96, v97
	v_subrev_u32_e32 v218, s12, v98
	global_store_dwordx4 v218, v[90:93], s[12:13]
	v_cvt_pk_bf16_f32 v82, v82, v83
	v_cvt_pk_bf16_f32 v83, v84, v85
	v_cvt_pk_bf16_f32 v84, v74, v75
	v_or_b32_e32 v74, 48, v146
	v_ashrrev_i32_e32 v75, 31, v74
	v_lshlrev_b64 v[74:75], 11, v[74:75]
	v_lshl_add_u64 v[74:75], s[12:13], 0, v[74:75]
	v_cvt_pk_bf16_f32 v85, v76, v77
	v_subrev_u32_e32 v218, s12, v98
	global_store_dwordx4 v218, v[82:85], s[12:13] offset:256
	s_nop 1
	v_lshl_add_u64 v[82:83], v[74:75], 0, v[150:151]
	v_cvt_pk_bf16_f32 v74, v86, v87
	v_cvt_pk_bf16_f32 v75, v88, v89
	v_cvt_pk_bf16_f32 v76, v78, v79
	v_cvt_pk_bf16_f32 v77, v80, v81
	v_subrev_u32_e32 v218, s12, v82
	global_store_dwordx4 v218, v[74:77], s[12:13]
	v_cvt_pk_bf16_f32 v70, v70, v71
	v_cvt_pk_bf16_f32 v71, v72, v73
	v_cvt_pk_bf16_f32 v72, v66, v67
	v_cvt_pk_bf16_f32 v73, v68, v69
	v_subrev_u32_e32 v218, s12, v82
	global_store_dwordx4 v218, v[70:73], s[12:13] offset:256
	v_cvt_pk_bf16_f32 v62, v62, v63
	v_cvt_pk_bf16_f32 v63, v64, v65
	v_cvt_pk_bf16_f32 v64, v58, v59
	v_add_co_u32_e32 v58, vcc, s77, v140
	v_lshl_add_u64 v[66:67], v[140:141], 0, s[80:81]
	s_nop 0
	v_addc_co_u32_e32 v59, vcc, 0, v141, vcc
	v_cvt_pk_bf16_f32 v65, v60, v61
	v_subrev_u32_e32 v218, s12, v58
	global_store_dwordx4 v218, v[62:65], s[12:13]
	v_cvt_pk_bf16_f32 v50, v50, v51
	v_cvt_pk_bf16_f32 v51, v52, v53
	v_cvt_pk_bf16_f32 v52, v42, v43
	v_cvt_pk_bf16_f32 v53, v44, v45
	v_subrev_u32_e32 v218, s12, v66
	global_store_dwordx4 v218, v[50:53], s[12:13] offset:256
	v_cvt_pk_bf16_f32 v42, v54, v55
	v_cvt_pk_bf16_f32 v43, v56, v57
	v_cvt_pk_bf16_f32 v44, v46, v47
	v_add_co_u32_e32 v46, vcc, s87, v140
	s_nop 0
	v_lshl_add_u64 v[50:51], v[140:141], 0, s[88:89]
	v_addc_co_u32_e32 v47, vcc, 0, v141, vcc
	v_cvt_pk_bf16_f32 v45, v48, v49
	v_subrev_u32_e32 v218, s12, v46
	global_store_dwordx4 v218, v[42:45], s[12:13]
	v_cvt_pk_bf16_f32 v34, v34, v35
	v_cvt_pk_bf16_f32 v35, v36, v37
	v_cvt_pk_bf16_f32 v36, v26, v27
	v_cvt_pk_bf16_f32 v37, v28, v29
	v_subrev_u32_e32 v218, s12, v50
	global_store_dwordx4 v218, v[34:37], s[12:13] offset:256
	v_cvt_pk_bf16_f32 v26, v38, v39
	v_cvt_pk_bf16_f32 v27, v40, v41
	v_cvt_pk_bf16_f32 v28, v30, v31
	v_add_co_u32_e32 v30, vcc, s94, v140
	s_nop 0
	v_lshl_add_u64 v[34:35], v[140:141], 0, s[90:91]
	v_addc_co_u32_e32 v31, vcc, 0, v141, vcc
	v_cvt_pk_bf16_f32 v29, v32, v33
	v_subrev_u32_e32 v218, s12, v30
	global_store_dwordx4 v218, v[26:29], s[12:13]
	v_cvt_pk_bf16_f32 v18, v18, v19
	v_cvt_pk_bf16_f32 v19, v20, v21
	v_cvt_pk_bf16_f32 v20, v10, v11
	v_cvt_pk_bf16_f32 v21, v12, v13
	v_subrev_u32_e32 v218, s12, v34
	global_store_dwordx4 v218, v[18:21], s[12:13] offset:256
	v_cvt_pk_bf16_f32 v10, v22, v23
	v_cvt_pk_bf16_f32 v11, v24, v25
	v_cvt_pk_bf16_f32 v12, v14, v15
	v_add_co_u32_e32 v14, vcc, s95, v140
	s_nop 0
	v_lshl_add_u64 v[18:19], v[140:141], 0, s[92:93]
	v_addc_co_u32_e32 v15, vcc, 0, v141, vcc
	s_and_b64 vcc, exec, s[6:7]
	s_mov_b64 s[6:7], -1
	v_cvt_pk_bf16_f32 v13, v16, v17
	v_subrev_u32_e32 v218, s12, v14
	global_store_dwordx4 v218, v[10:13], s[12:13]
	v_cvt_pk_bf16_f32 v6, v6, v7
	v_cvt_pk_bf16_f32 v7, v8, v9
	v_cvt_pk_bf16_f32 v8, v2, v3
	v_cvt_pk_bf16_f32 v9, v4, v5
	v_subrev_u32_e32 v218, s12, v18
	global_store_dwordx4 v218, v[6:9], s[12:13] offset:256
	s_cbranch_vccnz .LBB0_691
	s_andn2_b64 vcc, exec, s[10:11]
	s_cbranch_vccnz .LBB0_690
	s_barrier
	s_branch .LBB0_690
